# k-blocked weight layout also for NSA_PACK compression-MLP layer-1 weights (WP1, K=2048) and its gather-GEMM loop
# speedup vs baseline: 1.0038x; 1.0038x over previous
.LBB0_594:
	s_andn2_b64 vcc, exec, s[0:1]
	s_cbranch_vccnz .LBB0_587
	s_ashr_i32 s0, s57, 5
	s_lshl_b32 s40, s0, 8
	s_add_i32 s0, s0, s52
	s_ashr_i32 s1, s0, 31
	s_lshl_b64 s[12:13], s[0:1], 20
	s_waitcnt vmcnt(15)
	v_mov_b32_e32 v18, v224
	s_add_u32 s42, s55, s12
	s_addc_u32 s43, s56, s13
	v_readfirstlane_b32 s70, v18
	v_bfe_u32 v19, v18, 4, 2
	s_waitcnt vmcnt(5)
	v_bfe_u32 v12, v18, 2, 4
	v_sub_u32_e32 v0, 0, v19
	s_and_b32 s41, s70, 0xffffffc0
	v_xor_b32_e32 v0, v18, v0
	v_or_b32_e32 v10, s41, v12
	s_lshl_b32 s12, s57, 7
	s_ashr_i32 s71, s70, 6
	v_lshlrev_b32_e32 v0, 3, v0
	v_min_i32_e32 v4, 0xff, v10
	v_or_b32_e32 v6, 16, v10
	v_or_b32_e32 v8, 32, v10
	v_or_b32_e32 v10, 48, v10
	s_ashr_i32 s41, s40, 31
	s_and_b32 s12, s12, 0xf80
	v_and_b32_e32 v143, 24, v0
	v_min_i32_e32 v6, 0xff, v6
	v_min_i32_e32 v8, 0xff, v8
	v_min_i32_e32 v10, 0xff, v10
	s_lshl_b32 s74, s71, 1
	s_lshl_b64 s[40:41], s[40:41], 1
	v_lshlrev_b32_e32 v0, 1, v143
	v_ashrrev_i32_e32 v5, 31, v4
	v_ashrrev_i32_e32 v7, 31, v6
	v_ashrrev_i32_e32 v9, 31, v8
	v_ashrrev_i32_e32 v11, 31, v10
	s_add_u32 s68, s4, s40
	v_lshl_add_u64 v[2:3], s[42:43], 0, v[0:1]
	v_lshlrev_b64 v[4:5], 6, v[4:5]
	v_lshlrev_b64 v[6:7], 6, v[6:7]
	v_lshlrev_b64 v[8:9], 6, v[8:9]
	v_lshlrev_b64 v[10:11], 6, v[10:11]
	v_or_b32_e32 v20, s12, v12
	s_addc_u32 s69, s5, s41
	s_lshl_b32 s41, s71, 7
	v_lshl_add_u64 v[4:5], v[2:3], 0, v[4:5]
	v_lshl_add_u64 v[6:7], v[2:3], 0, v[6:7]
	v_lshl_add_u64 v[8:9], v[2:3], 0, v[8:9]
	v_lshl_add_u64 v[2:3], v[2:3], 0, v[10:11]
	v_lshl_add_u32 v10, v20, 2, s41
	v_and_b32_e32 v144, 0xffffffb0, v10
	v_mov_b64_e32 v[10:11], s[68:69]
	s_waitcnt vmcnt(1)
	v_lshlrev_b32_e32 v14, 5, v18
	v_mad_i64_i32 v[12:13], s[42:43], v144, s16, v[10:11]
	v_and_b32_e32 v14, 0x180, v14
	v_mov_b32_e32 v15, v1
	v_lshl_add_u64 v[12:13], v[12:13], 0, v[14:15]
	v_lshl_add_u64 v[12:13], v[12:13], 0, v[0:1]
	s_waitcnt vmcnt(0)
	s_waitcnt lgkmcnt(0)
	s_barrier
	v_lshl_add_u64 v[16:17], v[12:13], 0, s[66:67]
	s_lshl_b32 s75, s74, 10
	s_mov_b32 s41, m0
	s_mov_b32 m0, s75
	s_nop 0
	global_load_lds_dwordx4 v[16:17], off
	s_mov_b32 m0, s41
	s_or_b32 s41, s74, 1
	v_lshl_add_u32 v16, s41, 4, v20
	v_bfe_u32 v17, v16, 2, 9
	s_movk_i32 s42, 0x1ff
	v_lshlrev_b32_e32 v20, 4, v17
	v_cmp_ne_u32_e32 vcc, s42, v17
	v_mov_b32_e32 v17, 0x1fe0
	v_lshlrev_b32_e32 v16, 2, v16
	v_cndmask_b32_e32 v17, v17, v20, vcc
	s_movk_i32 s42, 0xe000
	v_and_or_b32 v145, v16, s42, v17
	v_mad_i64_i32 v[10:11], s[42:43], v145, s16, v[10:11]
	v_lshl_add_u64 v[10:11], v[10:11], 0, v[14:15]
	v_lshl_add_u64 v[10:11], v[10:11], 0, v[0:1]
	v_lshl_add_u64 v[16:17], v[10:11], 0, s[66:67]
	s_lshl_b32 s41, s41, 10
	s_mov_b32 s42, m0
	s_mov_b32 m0, s41
	s_nop 0
	global_load_lds_dwordx4 v[16:17], off
	s_mov_b32 m0, s42
	s_lshl_b32 s43, s71, 12
	s_add_i32 s42, s43, 0x2000
	s_mov_b32 s74, m0
	s_mov_b32 m0, s42
	s_nop 0
	global_load_lds_dwordx4 v[4:5], off
	s_mov_b32 m0, s74
	s_add_i32 s74, s43, 0x2400
	s_mov_b32 s76, m0
	s_mov_b32 m0, s74
	s_nop 0
	global_load_lds_dwordx4 v[6:7], off
	s_mov_b32 m0, s76
	s_add_i32 s74, s43, 0x2800
	s_mov_b32 s76, m0
	s_mov_b32 m0, s74
	s_nop 0
	global_load_lds_dwordx4 v[8:9], off
	s_mov_b32 m0, s76
	s_add_i32 s74, s43, 0x2c00
	s_mov_b32 s76, m0
	s_mov_b32 m0, s74
	s_nop 0
	global_load_lds_dwordx4 v[2:3], off
	s_mov_b32 m0, s76
	s_mov_b64 s[82:83], 0x840
	v_lshl_add_u64 v[12:13], v[12:13], 0, s[82:83]
	s_addk_i32 s75, 0x6000
	s_mov_b32 s74, m0
	s_mov_b32 m0, s75
	s_nop 0
	global_load_lds_dwordx4 v[12:13], off
	s_mov_b32 m0, s74
	v_lshl_add_u64 v[10:11], v[10:11], 0, s[82:83]
	s_add_i32 s74, s41, 0x6000
	s_mov_b32 s75, m0
	s_mov_b32 m0, s74
	s_nop 0
	global_load_lds_dwordx4 v[10:11], off
	s_mov_b32 m0, s75
	s_mov_b32 s100, 0x4000
	s_mov_b32 s101, 0
	v_lshl_add_u64 v[10:11], v[4:5], 0, s[100:101]
	s_add_i32 s74, s43, 0x8000
	s_mov_b32 s75, m0
	s_mov_b32 m0, s74
	s_nop 0
	global_load_lds_dwordx4 v[10:11], off
	s_mov_b32 m0, s75
	v_lshl_add_u64 v[10:11], v[6:7], 0, s[100:101]
	s_add_i32 s74, s43, 0x8400
	s_mov_b32 s75, m0
	s_mov_b32 m0, s74
	s_nop 0
	global_load_lds_dwordx4 v[10:11], off
	s_mov_b32 m0, s75
	v_lshl_add_u64 v[10:11], v[8:9], 0, s[100:101]
	s_add_i32 s74, s43, 0x8800
	s_mov_b32 s75, m0
	s_mov_b32 m0, s74
	s_nop 0
	global_load_lds_dwordx4 v[10:11], off
	s_mov_b32 m0, s75
	v_lshl_add_u64 v[10:11], v[2:3], 0, s[100:101]
	s_add_i32 s43, s43, 0x8c00
	s_mov_b32 s74, m0
	s_mov_b32 m0, s43
	s_nop 0
	global_load_lds_dwordx4 v[10:11], off
	s_mov_b32 m0, s74
	v_lshrrev_b32_e32 v10, 2, v18
	v_sub_u32_e32 v10, 0, v10
	v_and_b32_e32 v0, 15, v18
	v_bitop3_b32 v10, v19, v10, 3 bitop3:0x78
	v_lshlrev_b32_e32 v146, 4, v10
	v_and_or_b32 v10, s70, 64, v0
	s_and_b32 s70, s70, 0x3ffff80
	v_or_b32_e32 v0, s70, v0
	s_mov_b32 s100, 0x8000
	v_lshl_add_u64 v[132:133], v[2:3], 0, s[100:101]
	v_mov_b32_e32 v2, 0
	s_mov_b32 s13, 0
	s_mov_b32 s40, 2
	s_mov_b32 s43, 64
	v_lshlrev_b32_e32 v147, 6, v10
	v_lshlrev_b32_e32 v148, 6, v0
	v_lshl_add_u64 v[130:131], s[68:69], 0, v[14:15]
	s_lshl_b32 s68, s71, 11
	v_lshl_add_u64 v[134:135], v[8:9], 0, s[100:101]
	v_lshl_add_u64 v[136:137], v[6:7], 0, s[100:101]
	v_lshl_add_u64 v[138:139], v[4:5], 0, s[100:101]
	s_mov_b32 s100, 0x4000
	v_mov_b32_e32 v3, v2
	v_mov_b32_e32 v4, v2
	v_mov_b32_e32 v5, v2
	v_mov_b32_e32 v6, v2
	v_mov_b32_e32 v7, v2
	v_mov_b32_e32 v8, v2
	v_mov_b32_e32 v9, v2
	v_mov_b32_e32 v10, v2
	v_mov_b32_e32 v11, v2
	v_mov_b32_e32 v12, v2
	v_mov_b32_e32 v13, v2
	v_mov_b32_e32 v14, v2
	v_mov_b32_e32 v15, v2
	v_mov_b32_e32 v16, v2
	v_mov_b32_e32 v17, v2
	v_mov_b32_e32 v18, v2
	v_mov_b32_e32 v19, v2
	v_mov_b32_e32 v20, v2
	v_mov_b32_e32 v21, v2
	v_mov_b32_e32 v22, v2
	v_mov_b32_e32 v23, v2
	v_mov_b32_e32 v24, v2
	v_mov_b32_e32 v25, v2
	v_mov_b32_e32 v26, v2
	v_mov_b32_e32 v27, v2
	v_mov_b32_e32 v28, v2
	v_mov_b32_e32 v29, v2
	v_mov_b32_e32 v30, v2
	v_mov_b32_e32 v31, v2
	v_mov_b32_e32 v32, v2
	v_mov_b32_e32 v33, v2
	v_mov_b32_e32 v34, v2
	v_mov_b32_e32 v35, v2
	v_mov_b32_e32 v36, v2
	v_mov_b32_e32 v37, v2
	v_mov_b32_e32 v38, v2
	v_mov_b32_e32 v39, v2
	v_mov_b32_e32 v40, v2
	v_mov_b32_e32 v41, v2
	v_mov_b32_e32 v42, v2
	v_mov_b32_e32 v43, v2
	v_mov_b32_e32 v44, v2
	v_mov_b32_e32 v45, v2
	s_waitcnt vmcnt(0)
	v_mov_b32_e32 v46, v2
	v_mov_b32_e32 v47, v2
	v_mov_b32_e32 v48, v2
	v_mov_b32_e32 v49, v2
	v_mov_b32_e32 v50, v2
	v_mov_b32_e32 v51, v2
	v_mov_b32_e32 v52, v2
	v_mov_b32_e32 v53, v2
	v_mov_b32_e32 v54, v2
	v_mov_b32_e32 v55, v2
	v_mov_b32_e32 v56, v2
	v_mov_b32_e32 v57, v2
	v_mov_b32_e32 v58, v2
	v_mov_b32_e32 v59, v2
	v_mov_b32_e32 v60, v2
	v_mov_b32_e32 v61, v2
	v_mov_b32_e32 v62, v2
	v_mov_b32_e32 v63, v2
	v_mov_b32_e32 v64, v2
	v_mov_b32_e32 v65, v2
	v_mov_b32_e32 v66, v2
	v_mov_b32_e32 v67, v2
	v_mov_b32_e32 v68, v2
	v_mov_b32_e32 v69, v2
	v_mov_b32_e32 v70, v2
	v_mov_b32_e32 v71, v2
	v_mov_b32_e32 v72, v2
	v_mov_b32_e32 v73, v2
	v_mov_b32_e32 v74, v2
	v_mov_b32_e32 v75, v2
	v_mov_b32_e32 v76, v2
	v_mov_b32_e32 v77, v2
	v_mov_b32_e32 v78, v2
	v_mov_b32_e32 v79, v2
	v_mov_b32_e32 v80, v2
	v_mov_b32_e32 v81, v2
	v_mov_b32_e32 v82, v2
	v_mov_b32_e32 v83, v2
	v_mov_b32_e32 v84, v2
	v_mov_b32_e32 v85, v2
	v_mov_b32_e32 v86, v2
	v_mov_b32_e32 v87, v2
	v_mov_b32_e32 v88, v2
	v_mov_b32_e32 v89, v2
	v_mov_b32_e32 v90, v2
	v_mov_b32_e32 v91, v2
	v_mov_b32_e32 v92, v2
	v_mov_b32_e32 v93, v2
	v_mov_b32_e32 v94, v2
	v_mov_b32_e32 v95, v2
	v_mov_b32_e32 v96, v2
	v_mov_b32_e32 v97, v2
	v_mov_b32_e32 v98, v2
	v_mov_b32_e32 v99, v2
	v_mov_b32_e32 v100, v2
	v_mov_b32_e32 v101, v2
	v_mov_b32_e32 v102, v2
	v_mov_b32_e32 v103, v2
	v_mov_b32_e32 v104, v2
	v_mov_b32_e32 v105, v2
	v_mov_b32_e32 v106, v2
	v_mov_b32_e32 v107, v2
	v_mov_b32_e32 v108, v2
	v_mov_b32_e32 v109, v2
	v_mov_b32_e32 v110, v2
	v_mov_b32_e32 v111, v2
	v_mov_b32_e32 v112, v2
	v_mov_b32_e32 v113, v2
	v_mov_b32_e32 v114, v2
	v_mov_b32_e32 v115, v2
	v_mov_b32_e32 v116, v2
	v_mov_b32_e32 v117, v2
	v_mov_b32_e32 v118, v2
	v_mov_b32_e32 v119, v2
	v_mov_b32_e32 v120, v2
	v_mov_b32_e32 v121, v2
	v_mov_b32_e32 v122, v2
	v_mov_b32_e32 v123, v2
	v_mov_b32_e32 v124, v2
	v_mov_b32_e32 v125, v2
	v_mov_b32_e32 v126, v2
	v_mov_b32_e32 v127, v2
	v_mov_b32_e32 v128, v2
	v_mov_b32_e32 v129, v2
.LBB0_596:
	s_mul_i32 s69, s13, 0x6000
	s_add_i32 s70, s69, 0xffffa000
	s_cmp_gt_i32 s13, 0
	s_cselect_b32 s74, s70, 0xc000
	s_lshr_b32 s75, s40, 1
	v_and_or_b32 v0, s43, 32, v143
	v_add_u32_e32 v149, s75, v144
	v_mad_i64_i32 v[150:151], s[70:71], v149, s16, v[130:131]
	v_lshlrev_b32_e32 v0, 1, v0
	v_lshl_add_u64 v[150:151], v[150:151], 0, v[0:1]
	s_waitcnt vmcnt(6)
	v_lshl_add_u64 v[150:151], v[150:151], 0, s[66:67]
	s_add_i32 s70, s74, s68
	v_add_u32_e32 v149, s75, v145
	s_waitcnt lgkmcnt(0)
	s_barrier
	s_mov_b32 s71, m0
	s_mov_b32 m0, s70
	s_nop 0
	global_load_lds_dwordx4 v[150:151], off
	s_mov_b32 m0, s71
	s_nop 0
	v_mad_i64_i32 v[150:151], s[70:71], v149, s16, v[130:131]
	v_lshl_add_u64 v[150:151], v[150:151], 0, v[0:1]
	v_lshl_add_u64 v[150:151], v[150:151], 0, s[66:67]
	s_add_i32 s70, s74, s41
	s_mov_b32 s71, m0
	s_mov_b32 m0, s70
	s_nop 0
	global_load_lds_dwordx4 v[150:151], off
	s_mov_b32 m0, s71
	s_add_i32 s70, s42, s74
	s_mov_b32 s71, m0
	s_mov_b32 m0, s70
	s_nop 0
	global_load_lds_dwordx4 v[138:139], off
	s_mov_b32 m0, s71
	s_add_i32 s71, s70, 0x400
	s_mov_b32 s74, m0
	s_mov_b32 m0, s71
	s_nop 0
	global_load_lds_dwordx4 v[136:137], off
	s_mov_b32 m0, s74
	s_add_i32 s71, s70, 0x800
	s_mov_b32 s74, m0
	s_mov_b32 m0, s71
	s_nop 0
	global_load_lds_dwordx4 v[134:135], off
	s_mov_b32 m0, s74
	v_or_b32_e32 v0, s69, v147
	s_addk_i32 s70, 0xc00
	s_mov_b32 s71, m0
	s_mov_b32 m0, s70
	s_nop 0
	global_load_lds_dwordx4 v[132:133], off
	s_mov_b32 m0, s71
	v_add_u32_e32 v0, v0, v146
	ds_read_b128 v[150:153], v0
	ds_read_b128 v[154:157], v0 offset:1024
	ds_read_b128 v[158:161], v0 offset:2048
	ds_read_b128 v[162:165], v0 offset:3072
	v_add3_u32 v0, s69, v148, v146
	ds_read_b128 v[166:169], v0 offset:8192
	ds_read_b128 v[170:173], v0 offset:9216
	ds_read_b128 v[174:177], v0 offset:10240
	ds_read_b128 v[178:181], v0 offset:11264
	ds_read_b128 v[182:185], v0 offset:12288
	ds_read_b128 v[186:189], v0 offset:13312
	ds_read_b128 v[190:193], v0 offset:14336
	ds_read_b128 v[198:201], v0 offset:15360
	s_waitcnt lgkmcnt(7)
	v_mfma_f32_16x16x32_bf16 v[126:129], v[166:169], v[150:153], v[126:129]
	v_mfma_f32_16x16x32_bf16 v[122:125], v[166:169], v[154:157], v[122:125]
	v_mfma_f32_16x16x32_bf16 v[118:121], v[166:169], v[158:161], v[118:121]
	v_mfma_f32_16x16x32_bf16 v[114:117], v[166:169], v[162:165], v[114:117]
	s_waitcnt lgkmcnt(6)
	v_mfma_f32_16x16x32_bf16 v[110:113], v[170:173], v[150:153], v[110:113]
	v_mfma_f32_16x16x32_bf16 v[106:109], v[170:173], v[154:157], v[106:109]
	v_mfma_f32_16x16x32_bf16 v[102:105], v[170:173], v[158:161], v[102:105]
	v_mfma_f32_16x16x32_bf16 v[98:101], v[170:173], v[162:165], v[98:101]
	s_waitcnt lgkmcnt(5)
	v_mfma_f32_16x16x32_bf16 v[94:97], v[174:177], v[150:153], v[94:97]
	v_mfma_f32_16x16x32_bf16 v[90:93], v[174:177], v[154:157], v[90:93]
	v_mfma_f32_16x16x32_bf16 v[86:89], v[174:177], v[158:161], v[86:89]
	v_mfma_f32_16x16x32_bf16 v[82:85], v[174:177], v[162:165], v[82:85]
	s_waitcnt lgkmcnt(4)
	v_mfma_f32_16x16x32_bf16 v[78:81], v[178:181], v[150:153], v[78:81]
	v_mfma_f32_16x16x32_bf16 v[74:77], v[178:181], v[154:157], v[74:77]
	v_mfma_f32_16x16x32_bf16 v[70:73], v[178:181], v[158:161], v[70:73]
	v_mfma_f32_16x16x32_bf16 v[66:69], v[178:181], v[162:165], v[66:69]
	s_waitcnt lgkmcnt(3)
	v_mfma_f32_16x16x32_bf16 v[62:65], v[182:185], v[150:153], v[62:65]
	v_mfma_f32_16x16x32_bf16 v[58:61], v[182:185], v[154:157], v[58:61]
	v_mfma_f32_16x16x32_bf16 v[54:57], v[182:185], v[158:161], v[54:57]
	v_mfma_f32_16x16x32_bf16 v[50:53], v[182:185], v[162:165], v[50:53]
	s_waitcnt lgkmcnt(2)
	v_mfma_f32_16x16x32_bf16 v[46:49], v[186:189], v[150:153], v[46:49]
	v_mfma_f32_16x16x32_bf16 v[42:45], v[186:189], v[154:157], v[42:45]
	v_mfma_f32_16x16x32_bf16 v[38:41], v[186:189], v[158:161], v[38:41]
	v_mfma_f32_16x16x32_bf16 v[34:37], v[186:189], v[162:165], v[34:37]
	s_waitcnt lgkmcnt(1)
	v_mfma_f32_16x16x32_bf16 v[30:33], v[190:193], v[150:153], v[30:33]
	v_mfma_f32_16x16x32_bf16 v[26:29], v[190:193], v[154:157], v[26:29]
	v_mfma_f32_16x16x32_bf16 v[22:25], v[190:193], v[158:161], v[22:25]
	v_mfma_f32_16x16x32_bf16 v[18:21], v[190:193], v[162:165], v[18:21]
	s_waitcnt lgkmcnt(0)
	v_mfma_f32_16x16x32_bf16 v[14:17], v[198:201], v[150:153], v[14:17]
	v_mfma_f32_16x16x32_bf16 v[10:13], v[198:201], v[154:157], v[10:13]
	v_mfma_f32_16x16x32_bf16 v[6:9], v[198:201], v[158:161], v[6:9]
	v_mfma_f32_16x16x32_bf16 v[2:5], v[198:201], v[162:165], v[2:5]
	s_add_i32 s69, s13, 1
	s_cmp_lg_u32 s13, 2
	s_cselect_b32 s13, s69, 0
	s_add_i32 s40, s40, 1
	s_add_i32 s43, s43, 32
	v_lshl_add_u64 v[132:133], v[132:133], 0, s[100:101]
	v_lshl_add_u64 v[134:135], v[134:135], 0, s[100:101]
	v_lshl_add_u64 v[136:137], v[136:137], 0, s[100:101]
	s_cmp_eq_u32 s40, 64
	v_lshl_add_u64 v[138:139], v[138:139], 0, s[100:101]
	s_cbranch_scc0 .LBB0_596
	s_waitcnt vmcnt(6)
	v_add_u32_e32 v0, v148, v146
	s_waitcnt lgkmcnt(0)
	s_barrier
	ds_read_b128 v[130:133], v0 offset:64512
	ds_read_b128 v[134:137], v0 offset:63488
	ds_read_b128 v[148:151], v0 offset:62464
	ds_read_b128 v[152:155], v0 offset:61440
	ds_read_b128 v[156:159], v0 offset:60416
	ds_read_b128 v[160:163], v0 offset:59392
	ds_read_b128 v[164:167], v0 offset:58368
	ds_read_b128 v[168:171], v0 offset:57344
	v_add_u32_e32 v138, v147, v146
	ds_read_b128 v[144:147], v138 offset:52224
	ds_read_b128 v[172:175], v138 offset:51200
	ds_read_b128 v[176:179], v138 offset:50176
	ds_read_b128 v[180:183], v138 offset:49152
	s_lshl_b32 s40, s0, 8
	s_lshl_b64 s[0:1], s[0:1], 15
	s_ashr_i32 s41, s40, 31
	s_waitcnt lgkmcnt(0)
	v_mfma_f32_16x16x32_bf16 v[126:129], v[168:171], v[180:183], v[126:129]
	v_mfma_f32_16x16x32_bf16 v[46:49], v[148:151], v[180:183], v[46:49]
	v_mfma_f32_16x16x32_bf16 v[42:45], v[148:151], v[176:179], v[42:45]
	v_mfma_f32_16x16x32_bf16 v[38:41], v[148:151], v[172:175], v[38:41]
	v_mfma_f32_16x16x32_bf16 v[34:37], v[148:151], v[144:147], v[34:37]
	v_mfma_f32_16x16x32_bf16 v[30:33], v[134:137], v[180:183], v[30:33]
	v_mfma_f32_16x16x32_bf16 v[26:29], v[134:137], v[176:179], v[26:29]
	v_mfma_f32_16x16x32_bf16 v[22:25], v[134:137], v[172:175], v[22:25]
	v_mfma_f32_16x16x32_bf16 v[18:21], v[134:137], v[144:147], v[18:21]
	v_mfma_f32_16x16x32_bf16 v[14:17], v[130:133], v[180:183], v[14:17]
	v_mfma_f32_16x16x32_bf16 v[10:13], v[130:133], v[176:179], v[10:13]
	v_mfma_f32_16x16x32_bf16 v[6:9], v[130:133], v[172:175], v[6:9]
	v_mfma_f32_16x16x32_bf16 v[2:5], v[130:133], v[144:147], v[2:5]
	v_mfma_f32_16x16x32_bf16 v[122:125], v[168:171], v[176:179], v[122:125]
	v_mfma_f32_16x16x32_bf16 v[118:121], v[168:171], v[172:175], v[118:121]
	v_mfma_f32_16x16x32_bf16 v[114:117], v[168:171], v[144:147], v[114:117]
	v_mfma_f32_16x16x32_bf16 v[110:113], v[164:167], v[180:183], v[110:113]
	v_mfma_f32_16x16x32_bf16 v[106:109], v[164:167], v[176:179], v[106:109]
	v_mfma_f32_16x16x32_bf16 v[102:105], v[164:167], v[172:175], v[102:105]
	v_mfma_f32_16x16x32_bf16 v[98:101], v[164:167], v[144:147], v[98:101]
	v_mfma_f32_16x16x32_bf16 v[94:97], v[160:163], v[180:183], v[94:97]
	v_mfma_f32_16x16x32_bf16 v[90:93], v[160:163], v[176:179], v[90:93]
	v_mfma_f32_16x16x32_bf16 v[86:89], v[160:163], v[172:175], v[86:89]
	v_mfma_f32_16x16x32_bf16 v[82:85], v[160:163], v[144:147], v[82:85]
	v_mfma_f32_16x16x32_bf16 v[78:81], v[156:159], v[180:183], v[78:81]
	v_mfma_f32_16x16x32_bf16 v[74:77], v[156:159], v[176:179], v[74:77]
	v_mfma_f32_16x16x32_bf16 v[70:73], v[156:159], v[172:175], v[70:73]
	v_mfma_f32_16x16x32_bf16 v[66:69], v[156:159], v[144:147], v[66:69]
	v_mfma_f32_16x16x32_bf16 v[62:65], v[152:155], v[180:183], v[62:65]
	v_mfma_f32_16x16x32_bf16 v[58:61], v[152:155], v[176:179], v[58:61]
	v_mfma_f32_16x16x32_bf16 v[54:57], v[152:155], v[172:175], v[54:57]
	v_mfma_f32_16x16x32_bf16 v[50:53], v[152:155], v[144:147], v[50:53]
	s_waitcnt vmcnt(0)
	s_waitcnt lgkmcnt(0)
	s_barrier
	ds_read_b128 v[130:133], v138
	ds_read_b128 v[134:137], v138 offset:1024
	ds_read_b128 v[144:147], v138 offset:2048
	ds_read_b128 v[148:151], v138 offset:3072
	ds_read_b128 v[152:155], v0 offset:8192
	ds_read_b128 v[156:159], v0 offset:9216
	ds_read_b128 v[160:163], v0 offset:10240
	ds_read_b128 v[164:167], v0 offset:11264
	ds_read_b128 v[168:171], v0 offset:12288
	ds_read_b128 v[172:175], v0 offset:13312
	ds_read_b128 v[176:179], v0 offset:14336
	ds_read_b128 v[180:183], v0 offset:15360
	s_lshl_b64 s[40:41], s[40:41], 2
	s_add_u32 s42, s14, s40
	s_addc_u32 s43, s15, s41
	s_add_u32 s40, s53, s0
	s_addc_u32 s41, s54, s1
	s_waitcnt lgkmcnt(2)
	v_mfma_f32_16x16x32_bf16 v[46:49], v[172:175], v[130:133], v[46:49]
	v_mfma_f32_16x16x32_bf16 v[42:45], v[172:175], v[134:137], v[42:45]
	v_mfma_f32_16x16x32_bf16 v[38:41], v[172:175], v[144:147], v[38:41]
	v_mfma_f32_16x16x32_bf16 v[34:37], v[172:175], v[148:151], v[34:37]
	s_waitcnt lgkmcnt(1)
	v_mfma_f32_16x16x32_bf16 v[30:33], v[176:179], v[130:133], v[30:33]
	v_mfma_f32_16x16x32_bf16 v[26:29], v[176:179], v[134:137], v[26:29]
	v_mfma_f32_16x16x32_bf16 v[22:25], v[176:179], v[144:147], v[22:25]
	v_mfma_f32_16x16x32_bf16 v[18:21], v[176:179], v[148:151], v[18:21]
	s_waitcnt lgkmcnt(0)
	v_mfma_f32_16x16x32_bf16 v[14:17], v[180:183], v[130:133], v[14:17]
	v_mfma_f32_16x16x32_bf16 v[10:13], v[180:183], v[134:137], v[10:13]
	v_mfma_f32_16x16x32_bf16 v[6:9], v[180:183], v[144:147], v[6:9]
	v_mfma_f32_16x16x32_bf16 v[2:5], v[180:183], v[148:151], v[2:5]
	v_mfma_f32_16x16x32_bf16 v[184:187], v[152:155], v[130:133], v[126:129]
	v_mfma_f32_16x16x32_bf16 v[122:125], v[152:155], v[134:137], v[122:125]
	v_mfma_f32_16x16x32_bf16 v[188:191], v[152:155], v[144:147], v[118:121]
	v_mfma_f32_16x16x32_bf16 v[114:117], v[152:155], v[148:151], v[114:117]
	v_mfma_f32_16x16x32_bf16 v[110:113], v[156:159], v[130:133], v[110:113]
	v_mfma_f32_16x16x32_bf16 v[106:109], v[156:159], v[134:137], v[106:109]
	v_mfma_f32_16x16x32_bf16 v[102:105], v[156:159], v[144:147], v[102:105]
	v_mfma_f32_16x16x32_bf16 v[98:101], v[156:159], v[148:151], v[98:101]
	v_mfma_f32_16x16x32_bf16 v[94:97], v[160:163], v[130:133], v[94:97]
	v_mfma_f32_16x16x32_bf16 v[90:93], v[160:163], v[134:137], v[90:93]
	v_mfma_f32_16x16x32_bf16 v[86:89], v[160:163], v[144:147], v[86:89]
	v_mfma_f32_16x16x32_bf16 v[82:85], v[160:163], v[148:151], v[82:85]
	v_mfma_f32_16x16x32_bf16 v[78:81], v[164:167], v[130:133], v[78:81]
	v_mfma_f32_16x16x32_bf16 v[74:77], v[164:167], v[134:137], v[74:77]
	v_mfma_f32_16x16x32_bf16 v[70:73], v[164:167], v[144:147], v[70:73]
	v_mfma_f32_16x16x32_bf16 v[66:69], v[164:167], v[148:151], v[66:69]
	v_mfma_f32_16x16x32_bf16 v[62:65], v[168:171], v[130:133], v[62:65]
	v_mfma_f32_16x16x32_bf16 v[58:61], v[168:171], v[134:137], v[58:61]
	v_mfma_f32_16x16x32_bf16 v[54:57], v[168:171], v[144:147], v[54:57]
	v_mfma_f32_16x16x32_bf16 v[50:53], v[168:171], v[148:151], v[50:53]
	v_mov_b32_e32 v129, v224
	s_movk_i32 s0, 0xff80
	v_bfe_u32 v0, v129, 4, 2
	v_lshlrev_b32_e32 v128, 2, v0
	v_and_or_b32 v126, v129, s0, v128
	v_ashrrev_i32_e32 v127, 31, v126
	v_lshl_add_u64 v[118:119], v[126:127], 2, s[42:43]
	s_barrier
	global_load_dwordx4 v[132:135], v[118:119], off
	v_and_b32_e32 v138, 0x4f, v129
	v_lshlrev_b32_e32 v0, 4, v0
	s_movk_i32 s0, 0x210
	s_cmp_gt_u32 s57, 31
	s_waitcnt vmcnt(0)
	v_pk_add_f32 v[120:121], v[184:185], v[132:133]
	s_nop 0
	v_pk_mul_f32 v[130:131], v[120:121], v[120:121]
	v_pk_add_f32 v[122:123], v[122:123], v[132:133]
	v_fmamk_f32 v127, v130, 0xbdd2d3e2, v251
	v_mul_f32_e32 v127, v120, v127
	v_exp_f32_e32 v127, v127
	v_pk_add_f32 v[114:115], v[114:115], v[132:133]
	v_add_f32_e32 v127, 1.0, v127
	v_rcp_f32_e32 v130, v127
	v_fmamk_f32 v127, v131, 0xbdd2d3e2, v251
	v_mul_f32_e32 v127, v121, v127
	v_exp_f32_e32 v127, v127
	s_nop 0
	v_add_f32_e32 v127, 1.0, v127
	v_rcp_f32_e32 v131, v127
	v_mul_u32_u24_e32 v127, 0x210, v138
	v_pk_mul_f32 v[120:121], v[120:121], v[130:131]
	v_pk_add_f32 v[130:131], v[186:187], v[134:135]
	v_cvt_pk_bf16_f32 v120, v120, v121
	v_pk_mul_f32 v[136:137], v[130:131], v[130:131]
	s_nop 0
	v_fmamk_f32 v121, v136, 0xbdd2d3e2, v251
	v_mul_f32_e32 v121, v130, v121
	v_exp_f32_e32 v121, v121
	s_nop 0
	v_add_f32_e32 v121, 1.0, v121
	v_rcp_f32_e32 v136, v121
	v_fmamk_f32 v121, v137, 0xbdd2d3e2, v251
	v_mul_f32_e32 v121, v131, v121
	v_exp_f32_e32 v121, v121
	s_nop 0
	v_add_f32_e32 v121, 1.0, v121
	v_rcp_f32_e32 v137, v121
	s_nop 0
	v_pk_mul_f32 v[130:131], v[130:131], v[136:137]
	s_nop 0
	v_cvt_pk_bf16_f32 v121, v130, v131
	v_lshl_add_u32 v130, v126, 1, v127
	v_pk_mul_f32 v[126:127], v[122:123], v[122:123]
	s_nop 0
	v_fmamk_f32 v126, v126, 0xbdd2d3e2, v251
	v_fmamk_f32 v127, v127, 0xbdd2d3e2, v251
	v_mul_f32_e32 v126, v122, v126
	v_mul_f32_e32 v127, v123, v127
	v_exp_f32_e32 v126, v126
	v_exp_f32_e32 v127, v127
	v_add_f32_e32 v126, 1.0, v126
	v_add_f32_e32 v127, 1.0, v127
	v_rcp_f32_e32 v126, v126
	v_rcp_f32_e32 v127, v127
	s_nop 0
	v_pk_mul_f32 v[122:123], v[122:123], v[126:127]
	s_nop 0
	v_cvt_pk_bf16_f32 v126, v122, v123
	v_pk_add_f32 v[122:123], v[124:125], v[134:135]
	s_nop 0
	v_pk_mul_f32 v[124:125], v[122:123], v[122:123]
	s_nop 0
	v_fmamk_f32 v124, v124, 0xbdd2d3e2, v251
	v_fmamk_f32 v125, v125, 0xbdd2d3e2, v251
	v_mul_f32_e32 v124, v122, v124
	v_mul_f32_e32 v125, v123, v125
	v_exp_f32_e32 v124, v124
	v_exp_f32_e32 v125, v125
	v_add_f32_e32 v124, 1.0, v124
	v_add_f32_e32 v125, 1.0, v125
	v_rcp_f32_e32 v124, v124
	v_rcp_f32_e32 v125, v125
	s_nop 0
	v_pk_mul_f32 v[122:123], v[122:123], v[124:125]
	s_nop 0
	v_cvt_pk_bf16_f32 v127, v122, v123
	v_pk_add_f32 v[122:123], v[188:189], v[132:133]
	s_nop 0
	v_pk_mul_f32 v[124:125], v[122:123], v[122:123]
	s_nop 0
	v_fmamk_f32 v124, v124, 0xbdd2d3e2, v251
	v_fmamk_f32 v125, v125, 0xbdd2d3e2, v251
	v_mul_f32_e32 v124, v122, v124
	v_mul_f32_e32 v125, v123, v125
	v_exp_f32_e32 v124, v124
	v_exp_f32_e32 v125, v125
	v_add_f32_e32 v124, 1.0, v124
	v_add_f32_e32 v125, 1.0, v125
	v_rcp_f32_e32 v124, v124
	v_rcp_f32_e32 v125, v125
	s_nop 0
	v_pk_mul_f32 v[122:123], v[122:123], v[124:125]
	s_nop 0
	v_cvt_pk_bf16_f32 v124, v122, v123
	v_pk_add_f32 v[122:123], v[190:191], v[134:135]
	s_nop 0
	v_pk_mul_f32 v[136:137], v[122:123], v[122:123]
	s_nop 0
	v_fmamk_f32 v125, v136, 0xbdd2d3e2, v251
	v_mul_f32_e32 v125, v122, v125
	v_exp_f32_e32 v125, v125
	s_nop 0
	v_add_f32_e32 v125, 1.0, v125
	v_rcp_f32_e32 v136, v125
	v_fmamk_f32 v125, v137, 0xbdd2d3e2, v251
	v_mul_f32_e32 v125, v123, v125
	v_exp_f32_e32 v125, v125
	s_nop 0
	v_add_f32_e32 v125, 1.0, v125
	v_rcp_f32_e32 v137, v125
	s_nop 0
	v_pk_mul_f32 v[122:123], v[122:123], v[136:137]
	s_nop 0
	v_cvt_pk_bf16_f32 v125, v122, v123
	v_pk_mul_f32 v[122:123], v[114:115], v[114:115]
	s_nop 0
	v_fmamk_f32 v122, v122, 0xbdd2d3e2, v251
	v_fmamk_f32 v123, v123, 0xbdd2d3e2, v251
	v_mul_f32_e32 v122, v114, v122
	v_mul_f32_e32 v123, v115, v123
	v_exp_f32_e32 v122, v122
	v_exp_f32_e32 v123, v123
	v_add_f32_e32 v122, 1.0, v122
	v_add_f32_e32 v123, 1.0, v123
	v_rcp_f32_e32 v122, v122
	v_rcp_f32_e32 v123, v123
	s_nop 0
	v_pk_mul_f32 v[114:115], v[114:115], v[122:123]
	s_nop 0
	v_cvt_pk_bf16_f32 v122, v114, v115
	v_pk_add_f32 v[114:115], v[116:117], v[134:135]
	s_nop 0
	v_pk_mul_f32 v[116:117], v[114:115], v[114:115]
	s_nop 0
	v_fmamk_f32 v116, v116, 0xbdd2d3e2, v251
	v_fmamk_f32 v117, v117, 0xbdd2d3e2, v251
	v_mul_f32_e32 v116, v114, v116
	v_mul_f32_e32 v117, v115, v117
	v_exp_f32_e32 v116, v116
	v_exp_f32_e32 v117, v117
	v_add_f32_e32 v116, 1.0, v116
	v_add_f32_e32 v117, 1.0, v117
	v_rcp_f32_e32 v116, v116
	v_rcp_f32_e32 v117, v117
	s_nop 0
	v_pk_mul_f32 v[114:115], v[114:115], v[116:117]
	s_nop 0
	v_cvt_pk_bf16_f32 v123, v114, v115
	global_load_dwordx4 v[114:117], v[118:119], off offset:64
	s_waitcnt vmcnt(0)
	v_pk_add_f32 v[110:111], v[110:111], v[114:115]
	s_nop 0
	v_pk_mul_f32 v[132:133], v[110:111], v[110:111]
	v_pk_add_f32 v[112:113], v[112:113], v[116:117]
	v_fmamk_f32 v131, v132, 0xbdd2d3e2, v251
	v_mul_f32_e32 v131, v110, v131
	v_exp_f32_e32 v131, v131
	v_pk_add_f32 v[106:107], v[106:107], v[114:115]
	v_pk_add_f32 v[102:103], v[102:103], v[114:115]
	v_pk_add_f32 v[98:99], v[98:99], v[114:115]
	v_add_f32_e32 v131, 1.0, v131
	v_rcp_f32_e32 v132, v131
	v_fmamk_f32 v131, v133, 0xbdd2d3e2, v251
	v_mul_f32_e32 v131, v111, v131
	v_exp_f32_e32 v131, v131
	v_pk_add_f32 v[100:101], v[100:101], v[116:117]
	v_add_f32_e32 v131, 1.0, v131
	v_rcp_f32_e32 v133, v131
	s_nop 0
	v_pk_mul_f32 v[110:111], v[110:111], v[132:133]
	v_pk_mul_f32 v[132:133], v[112:113], v[112:113]
	v_cvt_pk_bf16_f32 v110, v110, v111
	v_fmamk_f32 v111, v132, 0xbdd2d3e2, v251
	v_mul_f32_e32 v111, v112, v111
	v_exp_f32_e32 v111, v111
	s_nop 0
	v_add_f32_e32 v111, 1.0, v111
	v_rcp_f32_e32 v132, v111
	v_fmamk_f32 v111, v133, 0xbdd2d3e2, v251
	v_mul_f32_e32 v111, v113, v111
	v_exp_f32_e32 v111, v111
	s_nop 0
	v_add_f32_e32 v111, 1.0, v111
	v_rcp_f32_e32 v133, v111
	s_nop 0
	v_pk_mul_f32 v[112:113], v[112:113], v[132:133]
	s_nop 0
	v_cvt_pk_bf16_f32 v111, v112, v113
	ds_write2_b64 v130, v[120:121], v[110:111] offset1:4
	v_pk_mul_f32 v[110:111], v[106:107], v[106:107]
	s_nop 0
	v_fmamk_f32 v110, v110, 0xbdd2d3e2, v251
	v_fmamk_f32 v111, v111, 0xbdd2d3e2, v251
	v_mul_f32_e32 v110, v106, v110
	v_mul_f32_e32 v111, v107, v111
	v_exp_f32_e32 v110, v110
	v_exp_f32_e32 v111, v111
	v_add_f32_e32 v110, 1.0, v110
	v_add_f32_e32 v111, 1.0, v111
	v_rcp_f32_e32 v110, v110
	v_rcp_f32_e32 v111, v111
	s_nop 0
	v_pk_mul_f32 v[106:107], v[106:107], v[110:111]
	s_nop 0
	v_cvt_pk_bf16_f32 v110, v106, v107
	v_pk_add_f32 v[106:107], v[108:109], v[116:117]
	s_nop 0
	v_pk_mul_f32 v[108:109], v[106:107], v[106:107]
	s_nop 0
	v_fmamk_f32 v108, v108, 0xbdd2d3e2, v251
	v_fmamk_f32 v109, v109, 0xbdd2d3e2, v251
	v_mul_f32_e32 v108, v106, v108
	v_mul_f32_e32 v109, v107, v109
	v_exp_f32_e32 v108, v108
	v_exp_f32_e32 v109, v109
	v_add_f32_e32 v108, 1.0, v108
	v_add_f32_e32 v109, 1.0, v109
	v_rcp_f32_e32 v108, v108
	v_rcp_f32_e32 v109, v109
	s_nop 0
	v_pk_mul_f32 v[106:107], v[106:107], v[108:109]
	v_pk_mul_f32 v[108:109], v[102:103], v[102:103]
	v_cvt_pk_bf16_f32 v111, v106, v107
	v_fmamk_f32 v107, v108, 0xbdd2d3e2, v251
	v_mul_f32_e32 v107, v102, v107
	v_exp_f32_e32 v107, v107
	v_add_u32_e32 v106, 0x2000, v130
	ds_write2_b64 v106, v[126:127], v[110:111] offset0:32 offset1:36
	v_add_f32_e32 v107, 1.0, v107
	v_rcp_f32_e32 v108, v107
	v_fmamk_f32 v107, v109, 0xbdd2d3e2, v251
	v_mul_f32_e32 v107, v103, v107
	v_exp_f32_e32 v107, v107
	s_nop 0
	v_add_f32_e32 v107, 1.0, v107
	v_rcp_f32_e32 v109, v107
	s_nop 0
	v_pk_mul_f32 v[102:103], v[102:103], v[108:109]
	s_nop 0
	v_cvt_pk_bf16_f32 v108, v102, v103
	v_pk_add_f32 v[102:103], v[104:105], v[116:117]
	s_nop 0
	v_pk_mul_f32 v[104:105], v[102:103], v[102:103]
	s_nop 0
	v_fmamk_f32 v104, v104, 0xbdd2d3e2, v251
	v_fmamk_f32 v105, v105, 0xbdd2d3e2, v251
	v_mul_f32_e32 v104, v102, v104
	v_mul_f32_e32 v105, v103, v105
	v_exp_f32_e32 v104, v104
	v_exp_f32_e32 v105, v105
	v_add_f32_e32 v104, 1.0, v104
	v_add_f32_e32 v105, 1.0, v105
	v_rcp_f32_e32 v104, v104
	v_rcp_f32_e32 v105, v105
	s_nop 0
	v_pk_mul_f32 v[102:103], v[102:103], v[104:105]
	s_nop 0
	v_cvt_pk_bf16_f32 v109, v102, v103
	v_add_u32_e32 v102, 0x4000, v130
	ds_write2_b64 v102, v[124:125], v[108:109] offset0:64 offset1:68
	global_load_dwordx4 v[108:111], v[118:119], off offset:128
	v_pk_mul_f32 v[104:105], v[98:99], v[98:99]
	s_waitcnt vmcnt(0)
	v_pk_add_f32 v[94:95], v[94:95], v[108:109]
	v_fmamk_f32 v103, v104, 0xbdd2d3e2, v251
	v_mul_f32_e32 v103, v98, v103
	v_exp_f32_e32 v103, v103
	v_pk_add_f32 v[90:91], v[90:91], v[108:109]
	v_pk_add_f32 v[86:87], v[86:87], v[108:109]
	v_pk_add_f32 v[82:83], v[82:83], v[108:109]
	v_add_f32_e32 v103, 1.0, v103
	v_rcp_f32_e32 v104, v103
	v_fmamk_f32 v103, v105, 0xbdd2d3e2, v251
	v_mul_f32_e32 v103, v99, v103
	v_exp_f32_e32 v103, v103
	s_nop 0
	v_add_f32_e32 v103, 1.0, v103
	v_rcp_f32_e32 v105, v103
	s_nop 0
	v_pk_mul_f32 v[98:99], v[98:99], v[104:105]
	v_pk_mul_f32 v[104:105], v[100:101], v[100:101]
	v_cvt_pk_bf16_f32 v98, v98, v99
	v_fmamk_f32 v99, v104, 0xbdd2d3e2, v251
	v_mul_f32_e32 v99, v100, v99
	v_exp_f32_e32 v99, v99
	s_nop 0
	v_add_f32_e32 v99, 1.0, v99
	v_rcp_f32_e32 v104, v99
	v_fmamk_f32 v99, v105, 0xbdd2d3e2, v251
	v_mul_f32_e32 v99, v101, v99
	v_exp_f32_e32 v99, v99
	s_nop 0
	v_add_f32_e32 v99, 1.0, v99
	v_rcp_f32_e32 v105, v99
	s_nop 0
	v_pk_mul_f32 v[100:101], v[100:101], v[104:105]
	s_nop 0
	v_cvt_pk_bf16_f32 v99, v100, v101
	v_add_u32_e32 v100, 0x6000, v130
	ds_write2_b64 v100, v[122:123], v[98:99] offset0:96 offset1:100
	v_pk_mul_f32 v[98:99], v[94:95], v[94:95]
	s_nop 0
	v_fmamk_f32 v98, v98, 0xbdd2d3e2, v251
	v_fmamk_f32 v99, v99, 0xbdd2d3e2, v251
	v_mul_f32_e32 v98, v94, v98
	v_mul_f32_e32 v99, v95, v99
	v_exp_f32_e32 v98, v98
	v_exp_f32_e32 v99, v99
	v_add_f32_e32 v98, 1.0, v98
	v_add_f32_e32 v99, 1.0, v99
	v_rcp_f32_e32 v98, v98
	v_rcp_f32_e32 v99, v99
	s_nop 0
	v_pk_mul_f32 v[94:95], v[94:95], v[98:99]
	s_nop 0
	v_cvt_pk_bf16_f32 v98, v94, v95
	v_pk_add_f32 v[94:95], v[96:97], v[110:111]
	s_nop 0
	v_pk_mul_f32 v[96:97], v[94:95], v[94:95]
	s_nop 0
	v_fmamk_f32 v96, v96, 0xbdd2d3e2, v251
	v_fmamk_f32 v97, v97, 0xbdd2d3e2, v251
	v_mul_f32_e32 v96, v94, v96
	v_mul_f32_e32 v97, v95, v97
	v_exp_f32_e32 v96, v96
	v_exp_f32_e32 v97, v97
	v_add_f32_e32 v96, 1.0, v96
	v_add_f32_e32 v97, 1.0, v97
	v_rcp_f32_e32 v96, v96
	v_rcp_f32_e32 v97, v97
	s_nop 0
	v_pk_mul_f32 v[94:95], v[94:95], v[96:97]
	s_nop 0
	v_cvt_pk_bf16_f32 v99, v94, v95
	v_pk_mul_f32 v[94:95], v[90:91], v[90:91]
	s_nop 0
	v_fmamk_f32 v94, v94, 0xbdd2d3e2, v251
	v_fmamk_f32 v95, v95, 0xbdd2d3e2, v251
	v_mul_f32_e32 v94, v90, v94
	v_mul_f32_e32 v95, v91, v95
	v_exp_f32_e32 v94, v94
	v_exp_f32_e32 v95, v95
	v_add_f32_e32 v94, 1.0, v94
	v_add_f32_e32 v95, 1.0, v95
	v_rcp_f32_e32 v94, v94
	v_rcp_f32_e32 v95, v95
	s_nop 0
	v_pk_mul_f32 v[90:91], v[90:91], v[94:95]
	s_nop 0
	v_cvt_pk_bf16_f32 v94, v90, v91
	v_pk_add_f32 v[90:91], v[92:93], v[110:111]
	s_nop 0
	v_pk_mul_f32 v[92:93], v[90:91], v[90:91]
	s_nop 0
	v_fmamk_f32 v92, v92, 0xbdd2d3e2, v251
	v_fmamk_f32 v93, v93, 0xbdd2d3e2, v251
	v_mul_f32_e32 v92, v90, v92
	v_mul_f32_e32 v93, v91, v93
	v_exp_f32_e32 v92, v92
	v_exp_f32_e32 v93, v93
	v_add_f32_e32 v92, 1.0, v92
	v_add_f32_e32 v93, 1.0, v93
	v_rcp_f32_e32 v92, v92
	v_rcp_f32_e32 v93, v93
	s_nop 0
	v_pk_mul_f32 v[90:91], v[90:91], v[92:93]
	s_nop 0
	v_cvt_pk_bf16_f32 v95, v90, v91
	v_pk_mul_f32 v[90:91], v[86:87], v[86:87]
	s_nop 0
	v_fmamk_f32 v90, v90, 0xbdd2d3e2, v251
	v_fmamk_f32 v91, v91, 0xbdd2d3e2, v251
	v_mul_f32_e32 v90, v86, v90
	v_mul_f32_e32 v91, v87, v91
	v_exp_f32_e32 v90, v90
	v_exp_f32_e32 v91, v91
	v_add_f32_e32 v90, 1.0, v90
	v_add_f32_e32 v91, 1.0, v91
	v_rcp_f32_e32 v90, v90
	v_rcp_f32_e32 v91, v91
	s_nop 0
	v_pk_mul_f32 v[86:87], v[86:87], v[90:91]
	s_nop 0
	v_cvt_pk_bf16_f32 v90, v86, v87
	v_pk_add_f32 v[86:87], v[88:89], v[110:111]
	s_nop 0
	v_pk_mul_f32 v[88:89], v[86:87], v[86:87]
	s_nop 0
	v_fmamk_f32 v88, v88, 0xbdd2d3e2, v251
	v_fmamk_f32 v89, v89, 0xbdd2d3e2, v251
	v_mul_f32_e32 v88, v86, v88
	v_mul_f32_e32 v89, v87, v89
	v_exp_f32_e32 v88, v88
	v_exp_f32_e32 v89, v89
	v_add_f32_e32 v88, 1.0, v88
	v_add_f32_e32 v89, 1.0, v89
	v_rcp_f32_e32 v88, v88
	v_rcp_f32_e32 v89, v89
	s_nop 0
	v_pk_mul_f32 v[86:87], v[86:87], v[88:89]
	s_nop 0
	v_cvt_pk_bf16_f32 v91, v86, v87
	v_pk_mul_f32 v[86:87], v[82:83], v[82:83]
	s_nop 0
	v_fmamk_f32 v86, v86, 0xbdd2d3e2, v251
	v_fmamk_f32 v87, v87, 0xbdd2d3e2, v251
	v_mul_f32_e32 v86, v82, v86
	v_mul_f32_e32 v87, v83, v87
	v_exp_f32_e32 v86, v86
	v_exp_f32_e32 v87, v87
	v_add_f32_e32 v86, 1.0, v86
	v_add_f32_e32 v87, 1.0, v87
	v_rcp_f32_e32 v86, v86
	v_rcp_f32_e32 v87, v87
	s_nop 0
	v_pk_mul_f32 v[82:83], v[82:83], v[86:87]
	s_nop 0
	v_cvt_pk_bf16_f32 v86, v82, v83
	v_pk_add_f32 v[82:83], v[84:85], v[110:111]
	s_nop 0
	v_pk_mul_f32 v[84:85], v[82:83], v[82:83]
	s_nop 0
	v_fmamk_f32 v84, v84, 0xbdd2d3e2, v251
	v_fmamk_f32 v85, v85, 0xbdd2d3e2, v251
	v_mul_f32_e32 v84, v82, v84
	v_mul_f32_e32 v85, v83, v85
	v_exp_f32_e32 v84, v84
	v_exp_f32_e32 v85, v85
	v_add_f32_e32 v84, 1.0, v84
	v_add_f32_e32 v85, 1.0, v85
	v_rcp_f32_e32 v84, v84
	v_rcp_f32_e32 v85, v85
	s_nop 0
	v_pk_mul_f32 v[82:83], v[82:83], v[84:85]
	s_nop 0
	v_cvt_pk_bf16_f32 v87, v82, v83
	global_load_dwordx4 v[82:85], v[118:119], off offset:192
	s_waitcnt vmcnt(0)
	v_pk_add_f32 v[78:79], v[78:79], v[82:83]
	s_nop 0
	v_pk_mul_f32 v[88:89], v[78:79], v[78:79]
	v_pk_add_f32 v[80:81], v[80:81], v[84:85]
	v_fmamk_f32 v88, v88, 0xbdd2d3e2, v251
	v_fmamk_f32 v89, v89, 0xbdd2d3e2, v251
	v_mul_f32_e32 v88, v78, v88
	v_mul_f32_e32 v89, v79, v89
	v_exp_f32_e32 v88, v88
	v_exp_f32_e32 v89, v89
	v_pk_add_f32 v[74:75], v[74:75], v[82:83]
	v_pk_add_f32 v[76:77], v[76:77], v[84:85]
	v_add_f32_e32 v88, 1.0, v88
	v_add_f32_e32 v89, 1.0, v89
	v_rcp_f32_e32 v88, v88
	v_rcp_f32_e32 v89, v89
	v_pk_add_f32 v[70:71], v[70:71], v[82:83]
	v_pk_add_f32 v[72:73], v[72:73], v[84:85]
	v_pk_add_f32 v[66:67], v[66:67], v[82:83]
	v_pk_mul_f32 v[78:79], v[78:79], v[88:89]
	v_pk_mul_f32 v[88:89], v[80:81], v[80:81]
	v_cvt_pk_bf16_f32 v78, v78, v79
	v_fmamk_f32 v79, v88, 0xbdd2d3e2, v251
	v_mul_f32_e32 v79, v80, v79
	v_exp_f32_e32 v79, v79
	v_pk_add_f32 v[68:69], v[68:69], v[84:85]
	v_add_f32_e32 v79, 1.0, v79
	v_rcp_f32_e32 v88, v79
	v_fmamk_f32 v79, v89, 0xbdd2d3e2, v251
	v_mul_f32_e32 v79, v81, v79
	v_exp_f32_e32 v79, v79
	s_nop 0
	v_add_f32_e32 v79, 1.0, v79
	v_rcp_f32_e32 v89, v79
	s_nop 0
	v_pk_mul_f32 v[80:81], v[80:81], v[88:89]
	s_nop 0
	v_cvt_pk_bf16_f32 v79, v80, v81
	ds_write2_b64 v130, v[98:99], v[78:79] offset0:8 offset1:12
	v_pk_mul_f32 v[78:79], v[74:75], v[74:75]
	s_nop 0
	v_fmamk_f32 v78, v78, 0xbdd2d3e2, v251
	v_fmamk_f32 v79, v79, 0xbdd2d3e2, v251
	v_mul_f32_e32 v78, v74, v78
	v_mul_f32_e32 v79, v75, v79
	v_exp_f32_e32 v78, v78
	v_exp_f32_e32 v79, v79
	v_add_f32_e32 v78, 1.0, v78
	v_add_f32_e32 v79, 1.0, v79
	v_rcp_f32_e32 v78, v78
	v_rcp_f32_e32 v79, v79
	s_nop 0
	v_pk_mul_f32 v[74:75], v[74:75], v[78:79]
	v_pk_mul_f32 v[78:79], v[76:77], v[76:77]
	v_cvt_pk_bf16_f32 v74, v74, v75
	v_fmamk_f32 v75, v78, 0xbdd2d3e2, v251
	v_mul_f32_e32 v75, v76, v75
	v_exp_f32_e32 v75, v75
	s_nop 0
	v_add_f32_e32 v75, 1.0, v75
	v_rcp_f32_e32 v78, v75
	v_fmamk_f32 v75, v79, 0xbdd2d3e2, v251
	v_mul_f32_e32 v75, v77, v75
	v_exp_f32_e32 v75, v75
	s_nop 0
	v_add_f32_e32 v75, 1.0, v75
	v_rcp_f32_e32 v79, v75
	s_nop 0
	v_pk_mul_f32 v[76:77], v[76:77], v[78:79]
	s_nop 0
	v_cvt_pk_bf16_f32 v75, v76, v77
	ds_write2_b64 v106, v[94:95], v[74:75] offset0:40 offset1:44
	v_pk_mul_f32 v[74:75], v[70:71], v[70:71]
	s_nop 0
	v_fmamk_f32 v74, v74, 0xbdd2d3e2, v251
	v_fmamk_f32 v75, v75, 0xbdd2d3e2, v251
	v_mul_f32_e32 v74, v70, v74
	v_mul_f32_e32 v75, v71, v75
	v_exp_f32_e32 v74, v74
	v_exp_f32_e32 v75, v75
	v_add_f32_e32 v74, 1.0, v74
	v_add_f32_e32 v75, 1.0, v75
	v_rcp_f32_e32 v74, v74
	v_rcp_f32_e32 v75, v75
	s_nop 0
	v_pk_mul_f32 v[70:71], v[70:71], v[74:75]
	v_pk_mul_f32 v[74:75], v[72:73], v[72:73]
	v_cvt_pk_bf16_f32 v70, v70, v71
	v_fmamk_f32 v71, v74, 0xbdd2d3e2, v251
	v_mul_f32_e32 v71, v72, v71
	v_exp_f32_e32 v71, v71
	s_nop 0
	v_add_f32_e32 v71, 1.0, v71
	v_rcp_f32_e32 v74, v71
	v_fmamk_f32 v71, v75, 0xbdd2d3e2, v251
	v_mul_f32_e32 v71, v73, v71
	v_exp_f32_e32 v71, v71
	s_nop 0
	v_add_f32_e32 v71, 1.0, v71
	v_rcp_f32_e32 v75, v71
	s_nop 0
	v_pk_mul_f32 v[72:73], v[72:73], v[74:75]
	s_nop 0
	v_cvt_pk_bf16_f32 v71, v72, v73
	ds_write2_b64 v102, v[90:91], v[70:71] offset0:72 offset1:76
	v_pk_mul_f32 v[70:71], v[66:67], v[66:67]
	s_nop 0
	v_fmamk_f32 v70, v70, 0xbdd2d3e2, v251
	v_fmamk_f32 v71, v71, 0xbdd2d3e2, v251
	v_mul_f32_e32 v70, v66, v70
	v_mul_f32_e32 v71, v67, v71
	v_exp_f32_e32 v70, v70
	v_exp_f32_e32 v71, v71
	v_add_f32_e32 v70, 1.0, v70
	v_add_f32_e32 v71, 1.0, v71
	v_rcp_f32_e32 v70, v70
	v_rcp_f32_e32 v71, v71
	s_nop 0
	v_pk_mul_f32 v[66:67], v[66:67], v[70:71]
	v_pk_mul_f32 v[70:71], v[68:69], v[68:69]
	v_cvt_pk_bf16_f32 v66, v66, v67
	v_fmamk_f32 v67, v70, 0xbdd2d3e2, v251
	v_mul_f32_e32 v67, v68, v67
	v_exp_f32_e32 v67, v67
	s_nop 0
	v_add_f32_e32 v67, 1.0, v67
	v_rcp_f32_e32 v70, v67
	v_fmamk_f32 v67, v71, 0xbdd2d3e2, v251
	v_mul_f32_e32 v67, v69, v67
	v_exp_f32_e32 v67, v67
	s_nop 0
	v_add_f32_e32 v67, 1.0, v67
	v_rcp_f32_e32 v71, v67
	s_nop 0
	v_pk_mul_f32 v[68:69], v[68:69], v[70:71]
	s_nop 0
	v_cvt_pk_bf16_f32 v67, v68, v69
	global_load_dwordx4 v[68:71], v[118:119], off offset:256
	ds_write2_b64 v100, v[86:87], v[66:67] offset0:104 offset1:108
	s_waitcnt vmcnt(0)
	v_pk_add_f32 v[62:63], v[62:63], v[68:69]
	s_nop 0
	v_pk_mul_f32 v[66:67], v[62:63], v[62:63]
	v_pk_add_f32 v[58:59], v[58:59], v[68:69]
	v_fmamk_f32 v66, v66, 0xbdd2d3e2, v251
	v_fmamk_f32 v67, v67, 0xbdd2d3e2, v251
	v_mul_f32_e32 v66, v62, v66
	v_mul_f32_e32 v67, v63, v67
	v_exp_f32_e32 v66, v66
	v_exp_f32_e32 v67, v67
	v_pk_add_f32 v[54:55], v[54:55], v[68:69]
	v_pk_add_f32 v[50:51], v[50:51], v[68:69]
	v_add_f32_e32 v66, 1.0, v66
	v_add_f32_e32 v67, 1.0, v67
	v_rcp_f32_e32 v66, v66
	v_rcp_f32_e32 v67, v67
	s_nop 0
	v_pk_mul_f32 v[62:63], v[62:63], v[66:67]
	s_nop 0
	v_cvt_pk_bf16_f32 v66, v62, v63
	v_pk_add_f32 v[62:63], v[64:65], v[70:71]
	s_nop 0
	v_pk_mul_f32 v[64:65], v[62:63], v[62:63]
	s_nop 0
	v_fmamk_f32 v64, v64, 0xbdd2d3e2, v251
	v_fmamk_f32 v65, v65, 0xbdd2d3e2, v251
	v_mul_f32_e32 v64, v62, v64
	v_mul_f32_e32 v65, v63, v65
	v_exp_f32_e32 v64, v64
	v_exp_f32_e32 v65, v65
	v_add_f32_e32 v64, 1.0, v64
	v_add_f32_e32 v65, 1.0, v65
	v_rcp_f32_e32 v64, v64
	v_rcp_f32_e32 v65, v65
	s_nop 0
	v_pk_mul_f32 v[62:63], v[62:63], v[64:65]
	s_nop 0
	v_cvt_pk_bf16_f32 v67, v62, v63
	v_pk_mul_f32 v[62:63], v[58:59], v[58:59]
	s_nop 0
	v_fmamk_f32 v62, v62, 0xbdd2d3e2, v251
	v_fmamk_f32 v63, v63, 0xbdd2d3e2, v251
	v_mul_f32_e32 v62, v58, v62
	v_mul_f32_e32 v63, v59, v63
	v_exp_f32_e32 v62, v62
	v_exp_f32_e32 v63, v63
	v_add_f32_e32 v62, 1.0, v62
	v_add_f32_e32 v63, 1.0, v63
	v_rcp_f32_e32 v62, v62
	v_rcp_f32_e32 v63, v63
	s_nop 0
	v_pk_mul_f32 v[58:59], v[58:59], v[62:63]
	s_nop 0
	v_cvt_pk_bf16_f32 v62, v58, v59
	v_pk_add_f32 v[58:59], v[60:61], v[70:71]
	s_nop 0
	v_pk_mul_f32 v[60:61], v[58:59], v[58:59]
	s_nop 0
	v_fmamk_f32 v60, v60, 0xbdd2d3e2, v251
	v_fmamk_f32 v61, v61, 0xbdd2d3e2, v251
	v_mul_f32_e32 v60, v58, v60
	v_mul_f32_e32 v61, v59, v61
	v_exp_f32_e32 v60, v60
	v_exp_f32_e32 v61, v61
	v_add_f32_e32 v60, 1.0, v60
	v_add_f32_e32 v61, 1.0, v61
	v_rcp_f32_e32 v60, v60
	v_rcp_f32_e32 v61, v61
	s_nop 0
	v_pk_mul_f32 v[58:59], v[58:59], v[60:61]
	s_nop 0
	v_cvt_pk_bf16_f32 v63, v58, v59
	v_pk_mul_f32 v[58:59], v[54:55], v[54:55]
	s_nop 0
	v_fmamk_f32 v58, v58, 0xbdd2d3e2, v251
	v_fmamk_f32 v59, v59, 0xbdd2d3e2, v251
	v_mul_f32_e32 v58, v54, v58
	v_mul_f32_e32 v59, v55, v59
	v_exp_f32_e32 v58, v58
	v_exp_f32_e32 v59, v59
	v_add_f32_e32 v58, 1.0, v58
	v_add_f32_e32 v59, 1.0, v59
	v_rcp_f32_e32 v58, v58
	v_rcp_f32_e32 v59, v59
	s_nop 0
	v_pk_mul_f32 v[54:55], v[54:55], v[58:59]
	s_nop 0
	v_cvt_pk_bf16_f32 v58, v54, v55
	v_pk_add_f32 v[54:55], v[56:57], v[70:71]
	s_nop 0
	v_pk_mul_f32 v[56:57], v[54:55], v[54:55]
	s_nop 0
	v_fmamk_f32 v56, v56, 0xbdd2d3e2, v251
	v_fmamk_f32 v57, v57, 0xbdd2d3e2, v251
	v_mul_f32_e32 v56, v54, v56
	v_mul_f32_e32 v57, v55, v57
	v_exp_f32_e32 v56, v56
	v_exp_f32_e32 v57, v57
	v_add_f32_e32 v56, 1.0, v56
	v_add_f32_e32 v57, 1.0, v57
	v_rcp_f32_e32 v56, v56
	v_rcp_f32_e32 v57, v57
	s_nop 0
	v_pk_mul_f32 v[54:55], v[54:55], v[56:57]
	s_nop 0
	v_cvt_pk_bf16_f32 v59, v54, v55
	v_pk_mul_f32 v[54:55], v[50:51], v[50:51]
	s_nop 0
	v_fmamk_f32 v54, v54, 0xbdd2d3e2, v251
	v_fmamk_f32 v55, v55, 0xbdd2d3e2, v251
	v_mul_f32_e32 v54, v50, v54
	v_mul_f32_e32 v55, v51, v55
	v_exp_f32_e32 v54, v54
	v_exp_f32_e32 v55, v55
	v_add_f32_e32 v54, 1.0, v54
	v_add_f32_e32 v55, 1.0, v55
	v_rcp_f32_e32 v54, v54
	v_rcp_f32_e32 v55, v55
	s_nop 0
	v_pk_mul_f32 v[50:51], v[50:51], v[54:55]
	s_nop 0
	v_cvt_pk_bf16_f32 v54, v50, v51
	v_pk_add_f32 v[50:51], v[52:53], v[70:71]
	s_nop 0
	v_pk_mul_f32 v[52:53], v[50:51], v[50:51]
	s_nop 0
	v_fmamk_f32 v52, v52, 0xbdd2d3e2, v251
	v_fmamk_f32 v53, v53, 0xbdd2d3e2, v251
	v_mul_f32_e32 v52, v50, v52
	v_mul_f32_e32 v53, v51, v53
	v_exp_f32_e32 v52, v52
	v_exp_f32_e32 v53, v53
	v_add_f32_e32 v52, 1.0, v52
	v_add_f32_e32 v53, 1.0, v53
	v_rcp_f32_e32 v52, v52
	v_rcp_f32_e32 v53, v53
	s_nop 0
	v_pk_mul_f32 v[50:51], v[50:51], v[52:53]
	s_nop 0
	v_cvt_pk_bf16_f32 v55, v50, v51
	global_load_dwordx4 v[50:53], v[118:119], off offset:320
	s_waitcnt vmcnt(0)
	v_pk_add_f32 v[46:47], v[46:47], v[50:51]
	s_nop 0
	v_pk_mul_f32 v[56:57], v[46:47], v[46:47]
	v_pk_add_f32 v[48:49], v[48:49], v[52:53]
	v_fmamk_f32 v56, v56, 0xbdd2d3e2, v251
	v_fmamk_f32 v57, v57, 0xbdd2d3e2, v251
	v_mul_f32_e32 v56, v46, v56
	v_mul_f32_e32 v57, v47, v57
	v_exp_f32_e32 v56, v56
	v_exp_f32_e32 v57, v57
	v_pk_add_f32 v[42:43], v[42:43], v[50:51]
	v_pk_add_f32 v[44:45], v[44:45], v[52:53]
	v_add_f32_e32 v56, 1.0, v56
	v_add_f32_e32 v57, 1.0, v57
	v_rcp_f32_e32 v56, v56
	v_rcp_f32_e32 v57, v57
	v_pk_add_f32 v[38:39], v[38:39], v[50:51]
	v_pk_add_f32 v[40:41], v[40:41], v[52:53]
	v_pk_add_f32 v[34:35], v[34:35], v[50:51]
	v_pk_mul_f32 v[46:47], v[46:47], v[56:57]
	v_pk_mul_f32 v[56:57], v[48:49], v[48:49]
	v_cvt_pk_bf16_f32 v46, v46, v47
	v_fmamk_f32 v47, v56, 0xbdd2d3e2, v251
	v_mul_f32_e32 v47, v48, v47
	v_exp_f32_e32 v47, v47
	v_pk_add_f32 v[36:37], v[36:37], v[52:53]
	v_add_f32_e32 v47, 1.0, v47
	v_rcp_f32_e32 v56, v47
	v_fmamk_f32 v47, v57, 0xbdd2d3e2, v251
	v_mul_f32_e32 v47, v49, v47
	v_exp_f32_e32 v47, v47
	s_nop 0
	v_add_f32_e32 v47, 1.0, v47
	v_rcp_f32_e32 v57, v47
	s_nop 0
	v_pk_mul_f32 v[48:49], v[48:49], v[56:57]
	s_nop 0
	v_cvt_pk_bf16_f32 v47, v48, v49
	ds_write2_b64 v130, v[66:67], v[46:47] offset0:16 offset1:20
	v_pk_mul_f32 v[46:47], v[42:43], v[42:43]
	s_nop 0
	v_fmamk_f32 v46, v46, 0xbdd2d3e2, v251
	v_fmamk_f32 v47, v47, 0xbdd2d3e2, v251
	v_mul_f32_e32 v46, v42, v46
	v_mul_f32_e32 v47, v43, v47
	v_exp_f32_e32 v46, v46
	v_exp_f32_e32 v47, v47
	v_add_f32_e32 v46, 1.0, v46
	v_add_f32_e32 v47, 1.0, v47
	v_rcp_f32_e32 v46, v46
	v_rcp_f32_e32 v47, v47
	s_nop 0
	v_pk_mul_f32 v[42:43], v[42:43], v[46:47]
	v_pk_mul_f32 v[46:47], v[44:45], v[44:45]
	v_cvt_pk_bf16_f32 v42, v42, v43
	v_fmamk_f32 v43, v46, 0xbdd2d3e2, v251
	v_mul_f32_e32 v43, v44, v43
	v_exp_f32_e32 v43, v43
	s_nop 0
	v_add_f32_e32 v43, 1.0, v43
	v_rcp_f32_e32 v46, v43
	v_fmamk_f32 v43, v47, 0xbdd2d3e2, v251
	v_mul_f32_e32 v43, v45, v43
	v_exp_f32_e32 v43, v43
	s_nop 0
	v_add_f32_e32 v43, 1.0, v43
	v_rcp_f32_e32 v47, v43
	s_nop 0
	v_pk_mul_f32 v[44:45], v[44:45], v[46:47]
	s_nop 0
	v_cvt_pk_bf16_f32 v43, v44, v45
	ds_write2_b64 v106, v[62:63], v[42:43] offset0:48 offset1:52
	v_pk_mul_f32 v[42:43], v[38:39], v[38:39]
	s_nop 0
	v_fmamk_f32 v42, v42, 0xbdd2d3e2, v251
	v_fmamk_f32 v43, v43, 0xbdd2d3e2, v251
	v_mul_f32_e32 v42, v38, v42
	v_mul_f32_e32 v43, v39, v43
	v_exp_f32_e32 v42, v42
	v_exp_f32_e32 v43, v43
	v_add_f32_e32 v42, 1.0, v42
	v_add_f32_e32 v43, 1.0, v43
	v_rcp_f32_e32 v42, v42
	v_rcp_f32_e32 v43, v43
	s_nop 0
	v_pk_mul_f32 v[38:39], v[38:39], v[42:43]
	v_pk_mul_f32 v[42:43], v[40:41], v[40:41]
	v_cvt_pk_bf16_f32 v38, v38, v39
	v_fmamk_f32 v39, v42, 0xbdd2d3e2, v251
	v_mul_f32_e32 v39, v40, v39
	v_exp_f32_e32 v39, v39
	s_nop 0
	v_add_f32_e32 v39, 1.0, v39
	v_rcp_f32_e32 v42, v39
	v_fmamk_f32 v39, v43, 0xbdd2d3e2, v251
	v_mul_f32_e32 v39, v41, v39
	v_exp_f32_e32 v39, v39
	s_nop 0
	v_add_f32_e32 v39, 1.0, v39
	v_rcp_f32_e32 v43, v39
	s_nop 0
	v_pk_mul_f32 v[40:41], v[40:41], v[42:43]
	s_nop 0
	v_cvt_pk_bf16_f32 v39, v40, v41
	ds_write2_b64 v102, v[58:59], v[38:39] offset0:80 offset1:84
	v_pk_mul_f32 v[38:39], v[34:35], v[34:35]
	s_nop 0
	v_fmamk_f32 v38, v38, 0xbdd2d3e2, v251
	v_fmamk_f32 v39, v39, 0xbdd2d3e2, v251
	v_mul_f32_e32 v38, v34, v38
	v_mul_f32_e32 v39, v35, v39
	v_exp_f32_e32 v38, v38
	v_exp_f32_e32 v39, v39
	v_add_f32_e32 v38, 1.0, v38
	v_add_f32_e32 v39, 1.0, v39
	v_rcp_f32_e32 v38, v38
	v_rcp_f32_e32 v39, v39
	s_nop 0
	v_pk_mul_f32 v[34:35], v[34:35], v[38:39]
	v_pk_mul_f32 v[38:39], v[36:37], v[36:37]
	v_cvt_pk_bf16_f32 v34, v34, v35
	v_fmamk_f32 v35, v38, 0xbdd2d3e2, v251
	v_mul_f32_e32 v35, v36, v35
	v_exp_f32_e32 v35, v35
	s_nop 0
	v_add_f32_e32 v35, 1.0, v35
	v_rcp_f32_e32 v38, v35
	v_fmamk_f32 v35, v39, 0xbdd2d3e2, v251
	v_mul_f32_e32 v35, v37, v35
	v_exp_f32_e32 v35, v35
	s_nop 0
	v_add_f32_e32 v35, 1.0, v35
	v_rcp_f32_e32 v39, v35
	s_nop 0
	v_pk_mul_f32 v[36:37], v[36:37], v[38:39]
	s_nop 0
	v_cvt_pk_bf16_f32 v35, v36, v37
	global_load_dwordx4 v[36:39], v[118:119], off offset:384
	ds_write2_b64 v100, v[54:55], v[34:35] offset0:112 offset1:116
	s_waitcnt vmcnt(0)
	v_pk_add_f32 v[30:31], v[30:31], v[36:37]
	s_nop 0
	v_pk_mul_f32 v[34:35], v[30:31], v[30:31]
	v_pk_add_f32 v[26:27], v[26:27], v[36:37]
	v_fmamk_f32 v34, v34, 0xbdd2d3e2, v251
	v_fmamk_f32 v35, v35, 0xbdd2d3e2, v251
	v_mul_f32_e32 v34, v30, v34
	v_mul_f32_e32 v35, v31, v35
	v_exp_f32_e32 v34, v34
	v_exp_f32_e32 v35, v35
	v_pk_add_f32 v[22:23], v[22:23], v[36:37]
	v_pk_add_f32 v[18:19], v[18:19], v[36:37]
	v_add_f32_e32 v34, 1.0, v34
	v_add_f32_e32 v35, 1.0, v35
	v_rcp_f32_e32 v34, v34
	v_rcp_f32_e32 v35, v35
	s_nop 0
	v_pk_mul_f32 v[30:31], v[30:31], v[34:35]
	s_nop 0
	v_cvt_pk_bf16_f32 v34, v30, v31
	v_pk_add_f32 v[30:31], v[32:33], v[38:39]
	s_nop 0
	v_pk_mul_f32 v[32:33], v[30:31], v[30:31]
	s_nop 0
	v_fmamk_f32 v32, v32, 0xbdd2d3e2, v251
	v_fmamk_f32 v33, v33, 0xbdd2d3e2, v251
	v_mul_f32_e32 v32, v30, v32
	v_mul_f32_e32 v33, v31, v33
	v_exp_f32_e32 v32, v32
	v_exp_f32_e32 v33, v33
	v_add_f32_e32 v32, 1.0, v32
	v_add_f32_e32 v33, 1.0, v33
	v_rcp_f32_e32 v32, v32
	v_rcp_f32_e32 v33, v33
	s_nop 0
	v_pk_mul_f32 v[30:31], v[30:31], v[32:33]
	s_nop 0
	v_cvt_pk_bf16_f32 v35, v30, v31
	v_pk_mul_f32 v[30:31], v[26:27], v[26:27]
	s_nop 0
	v_fmamk_f32 v30, v30, 0xbdd2d3e2, v251
	v_fmamk_f32 v31, v31, 0xbdd2d3e2, v251
	v_mul_f32_e32 v30, v26, v30
	v_mul_f32_e32 v31, v27, v31
	v_exp_f32_e32 v30, v30
	v_exp_f32_e32 v31, v31
	v_add_f32_e32 v30, 1.0, v30
	v_add_f32_e32 v31, 1.0, v31
	v_rcp_f32_e32 v30, v30
	v_rcp_f32_e32 v31, v31
	s_nop 0
	v_pk_mul_f32 v[26:27], v[26:27], v[30:31]
	s_nop 0
	v_cvt_pk_bf16_f32 v30, v26, v27
	v_pk_add_f32 v[26:27], v[28:29], v[38:39]
	s_nop 0
	v_pk_mul_f32 v[28:29], v[26:27], v[26:27]
	s_nop 0
	v_fmamk_f32 v28, v28, 0xbdd2d3e2, v251
	v_fmamk_f32 v29, v29, 0xbdd2d3e2, v251
	v_mul_f32_e32 v28, v26, v28
	v_mul_f32_e32 v29, v27, v29
	v_exp_f32_e32 v28, v28
	v_exp_f32_e32 v29, v29
	v_add_f32_e32 v28, 1.0, v28
	v_add_f32_e32 v29, 1.0, v29
	v_rcp_f32_e32 v28, v28
	v_rcp_f32_e32 v29, v29
	s_nop 0
	v_pk_mul_f32 v[26:27], v[26:27], v[28:29]
	s_nop 0
	v_cvt_pk_bf16_f32 v31, v26, v27
	v_pk_mul_f32 v[26:27], v[22:23], v[22:23]
	s_nop 0
	v_fmamk_f32 v26, v26, 0xbdd2d3e2, v251
	v_fmamk_f32 v27, v27, 0xbdd2d3e2, v251
	v_mul_f32_e32 v26, v22, v26
	v_mul_f32_e32 v27, v23, v27
	v_exp_f32_e32 v26, v26
	v_exp_f32_e32 v27, v27
	v_add_f32_e32 v26, 1.0, v26
	v_add_f32_e32 v27, 1.0, v27
	v_rcp_f32_e32 v26, v26
	v_rcp_f32_e32 v27, v27
	s_nop 0
	v_pk_mul_f32 v[22:23], v[22:23], v[26:27]
	s_nop 0
	v_cvt_pk_bf16_f32 v26, v22, v23
	v_pk_add_f32 v[22:23], v[24:25], v[38:39]
	s_nop 0
	v_pk_mul_f32 v[24:25], v[22:23], v[22:23]
	s_nop 0
	v_fmamk_f32 v24, v24, 0xbdd2d3e2, v251
	v_fmamk_f32 v25, v25, 0xbdd2d3e2, v251
	v_mul_f32_e32 v24, v22, v24
	v_mul_f32_e32 v25, v23, v25
	v_exp_f32_e32 v24, v24
	v_exp_f32_e32 v25, v25
	v_add_f32_e32 v24, 1.0, v24
	v_add_f32_e32 v25, 1.0, v25
	v_rcp_f32_e32 v24, v24
	v_rcp_f32_e32 v25, v25
	s_nop 0
	v_pk_mul_f32 v[22:23], v[22:23], v[24:25]
	s_nop 0
	v_cvt_pk_bf16_f32 v27, v22, v23
	v_pk_mul_f32 v[22:23], v[18:19], v[18:19]
	s_nop 0
	v_fmamk_f32 v22, v22, 0xbdd2d3e2, v251
	v_fmamk_f32 v23, v23, 0xbdd2d3e2, v251
	v_mul_f32_e32 v22, v18, v22
	v_mul_f32_e32 v23, v19, v23
	v_exp_f32_e32 v22, v22
	v_exp_f32_e32 v23, v23
	v_add_f32_e32 v22, 1.0, v22
	v_add_f32_e32 v23, 1.0, v23
	v_rcp_f32_e32 v22, v22
	v_rcp_f32_e32 v23, v23
	s_nop 0
	v_pk_mul_f32 v[18:19], v[18:19], v[22:23]
	s_nop 0
	v_cvt_pk_bf16_f32 v22, v18, v19
	v_pk_add_f32 v[18:19], v[20:21], v[38:39]
	s_nop 0
	v_pk_mul_f32 v[20:21], v[18:19], v[18:19]
	s_nop 0
	v_fmamk_f32 v20, v20, 0xbdd2d3e2, v251
	v_fmamk_f32 v21, v21, 0xbdd2d3e2, v251
	v_mul_f32_e32 v20, v18, v20
	v_mul_f32_e32 v21, v19, v21
	v_exp_f32_e32 v20, v20
	v_exp_f32_e32 v21, v21
	v_add_f32_e32 v20, 1.0, v20
	v_add_f32_e32 v21, 1.0, v21
	v_rcp_f32_e32 v20, v20
	v_rcp_f32_e32 v21, v21
	s_nop 0
	v_pk_mul_f32 v[18:19], v[18:19], v[20:21]
	s_nop 0
	v_cvt_pk_bf16_f32 v23, v18, v19
	global_load_dwordx4 v[18:21], v[118:119], off offset:448
	s_waitcnt vmcnt(0)
	v_pk_add_f32 v[14:15], v[14:15], v[18:19]
	s_nop 0
	v_pk_mul_f32 v[24:25], v[14:15], v[14:15]
	v_pk_add_f32 v[16:17], v[16:17], v[20:21]
	v_fmamk_f32 v24, v24, 0xbdd2d3e2, v251
	v_fmamk_f32 v25, v25, 0xbdd2d3e2, v251
	v_mul_f32_e32 v24, v14, v24
	v_mul_f32_e32 v25, v15, v25
	v_exp_f32_e32 v24, v24
	v_exp_f32_e32 v25, v25
	v_pk_add_f32 v[10:11], v[10:11], v[18:19]
	v_pk_add_f32 v[12:13], v[12:13], v[20:21]
	v_add_f32_e32 v24, 1.0, v24
	v_add_f32_e32 v25, 1.0, v25
	v_rcp_f32_e32 v24, v24
	v_rcp_f32_e32 v25, v25
	v_pk_add_f32 v[6:7], v[6:7], v[18:19]
	v_pk_add_f32 v[8:9], v[8:9], v[20:21]
	v_pk_add_f32 v[2:3], v[2:3], v[18:19]
	v_pk_mul_f32 v[14:15], v[14:15], v[24:25]
	v_pk_mul_f32 v[24:25], v[16:17], v[16:17]
	v_cvt_pk_bf16_f32 v14, v14, v15
	v_fmamk_f32 v15, v24, 0xbdd2d3e2, v251
	v_mul_f32_e32 v15, v16, v15
	v_exp_f32_e32 v15, v15
	v_pk_add_f32 v[4:5], v[4:5], v[20:21]
	v_add_f32_e32 v15, 1.0, v15
	v_rcp_f32_e32 v24, v15
	v_fmamk_f32 v15, v25, 0xbdd2d3e2, v251
	v_mul_f32_e32 v15, v17, v15
	v_exp_f32_e32 v15, v15
	s_nop 0
	v_add_f32_e32 v15, 1.0, v15
	v_rcp_f32_e32 v25, v15
	s_nop 0
	v_pk_mul_f32 v[16:17], v[16:17], v[24:25]
	s_nop 0
	v_cvt_pk_bf16_f32 v15, v16, v17
	ds_write2_b64 v130, v[34:35], v[14:15] offset0:24 offset1:28
	v_pk_mul_f32 v[14:15], v[10:11], v[10:11]
	v_and_b32_e32 v34, 15, v129
	v_fmamk_f32 v14, v14, 0xbdd2d3e2, v251
	v_fmamk_f32 v15, v15, 0xbdd2d3e2, v251
	v_mul_f32_e32 v14, v10, v14
	v_mul_f32_e32 v15, v11, v15
	v_exp_f32_e32 v14, v14
	v_exp_f32_e32 v15, v15
	v_add_f32_e32 v14, 1.0, v14
	v_add_f32_e32 v15, 1.0, v15
	v_rcp_f32_e32 v14, v14
	v_rcp_f32_e32 v15, v15
	s_nop 0
	v_pk_mul_f32 v[10:11], v[10:11], v[14:15]
	v_pk_mul_f32 v[14:15], v[12:13], v[12:13]
	v_cvt_pk_bf16_f32 v10, v10, v11
	v_fmamk_f32 v11, v14, 0xbdd2d3e2, v251
	v_mul_f32_e32 v11, v12, v11
	v_exp_f32_e32 v11, v11
	s_nop 0
	v_add_f32_e32 v11, 1.0, v11
	v_rcp_f32_e32 v14, v11
	v_fmamk_f32 v11, v15, 0xbdd2d3e2, v251
	v_mul_f32_e32 v11, v13, v11
	v_exp_f32_e32 v11, v11
	s_nop 0
	v_add_f32_e32 v11, 1.0, v11
	v_rcp_f32_e32 v15, v11
	s_nop 0
	v_pk_mul_f32 v[12:13], v[12:13], v[14:15]
	s_nop 0
	v_cvt_pk_bf16_f32 v11, v12, v13
	ds_write2_b64 v106, v[30:31], v[10:11] offset0:56 offset1:60
	v_pk_mul_f32 v[10:11], v[6:7], v[6:7]
	s_nop 0
	v_fmamk_f32 v10, v10, 0xbdd2d3e2, v251
	v_fmamk_f32 v11, v11, 0xbdd2d3e2, v251
	v_mul_f32_e32 v10, v6, v10
	v_mul_f32_e32 v11, v7, v11
	v_exp_f32_e32 v10, v10
	v_exp_f32_e32 v11, v11
	v_add_f32_e32 v10, 1.0, v10
	v_add_f32_e32 v11, 1.0, v11
	v_rcp_f32_e32 v10, v10
	v_rcp_f32_e32 v11, v11
	s_nop 0
	v_pk_mul_f32 v[6:7], v[6:7], v[10:11]
	v_pk_mul_f32 v[10:11], v[8:9], v[8:9]
	v_cvt_pk_bf16_f32 v6, v6, v7
	v_fmamk_f32 v7, v10, 0xbdd2d3e2, v251
	v_mul_f32_e32 v7, v8, v7
	v_exp_f32_e32 v7, v7
	s_nop 0
	v_add_f32_e32 v7, 1.0, v7
	v_rcp_f32_e32 v10, v7
	v_fmamk_f32 v7, v11, 0xbdd2d3e2, v251
	v_mul_f32_e32 v7, v9, v7
	v_exp_f32_e32 v7, v7
	s_nop 0
	v_add_f32_e32 v7, 1.0, v7
	v_rcp_f32_e32 v11, v7
	s_nop 0
	v_pk_mul_f32 v[8:9], v[8:9], v[10:11]
	s_nop 0
	v_cvt_pk_bf16_f32 v7, v8, v9
	ds_write2_b64 v102, v[26:27], v[6:7] offset0:88 offset1:92
	v_pk_mul_f32 v[6:7], v[2:3], v[2:3]
	v_lshl_add_u64 v[10:11], s[40:41], 0, v[0:1]
	v_fmamk_f32 v6, v6, 0xbdd2d3e2, v251
	v_fmamk_f32 v7, v7, 0xbdd2d3e2, v251
	v_mul_f32_e32 v6, v2, v6
	v_mul_f32_e32 v7, v3, v7
	v_exp_f32_e32 v6, v6
	v_exp_f32_e32 v7, v7
	v_lshl_add_u64 v[68:69], v[10:11], 0, 64
	v_add_f32_e32 v6, 1.0, v6
	v_add_f32_e32 v7, 1.0, v7
	v_rcp_f32_e32 v6, v6
	v_rcp_f32_e32 v7, v7
	s_nop 0
	v_pk_mul_f32 v[2:3], v[2:3], v[6:7]
	v_pk_mul_f32 v[6:7], v[4:5], v[4:5]
	v_cvt_pk_bf16_f32 v2, v2, v3
	v_fmamk_f32 v3, v6, 0xbdd2d3e2, v251
	v_mul_f32_e32 v3, v4, v3
	v_exp_f32_e32 v3, v3
	s_nop 0
	v_add_f32_e32 v3, 1.0, v3
	v_rcp_f32_e32 v6, v3
	v_fmamk_f32 v3, v7, 0xbdd2d3e2, v251
	v_mul_f32_e32 v3, v5, v3
	v_exp_f32_e32 v3, v3
	s_nop 0
	v_add_f32_e32 v3, 1.0, v3
	v_rcp_f32_e32 v7, v3
	s_nop 0
	v_pk_mul_f32 v[4:5], v[4:5], v[6:7]
	s_nop 0
	v_cvt_pk_bf16_f32 v3, v4, v5
	ds_write2_b64 v100, v[22:23], v[2:3] offset0:120 offset1:124
	v_ashrrev_i32_e32 v2, 1, v129
	v_and_b32_e32 v35, 0xffffffe0, v2
	v_or_b32_e32 v2, v35, v34
	v_lshlrev_b32_e32 v6, 9, v34
	v_mad_u64_u32 v[12:13], s[0:1], v2, s0, v[0:1]
	v_mov_b32_e32 v7, v1
	v_or_b32_e32 v2, 0x2000, v6
	v_mov_b32_e32 v3, v1
	v_lshl_add_u64 v[8:9], v[10:11], 0, v[6:7]
	v_lshl_add_u64 v[4:5], v[10:11], 0, v[2:3]
	s_waitcnt lgkmcnt(0)
	s_barrier
	ds_read_b128 v[14:17], v12
	ds_read_b128 v[18:21], v12 offset:8448
	global_load_dwordx4 v[22:25], v[8:9], off
	global_load_dwordx4 v[26:29], v[4:5], off
	v_or_b32_e32 v4, 0x4000, v6
	v_mov_b32_e32 v5, v1
	v_or_b32_e32 v6, 0x6000, v6
	v_lshl_add_u64 v[30:31], v[10:11], 0, v[4:5]
	v_lshl_add_u64 v[36:37], v[10:11], 0, v[6:7]
	global_load_dwordx4 v[30:33], v[30:31], off
	v_lshl_add_u64 v[60:61], v[68:69], 0, v[2:3]
	global_load_dwordx4 v[36:39], v[36:37], off
	v_lshl_add_u64 v[64:65], v[68:69], 0, v[4:5]
	v_lshl_add_u64 v[68:69], v[68:69], 0, v[6:7]
	s_waitcnt vmcnt(3) lgkmcnt(1)
	v_mfma_f32_16x16x32_bf16 v[40:43], v[22:25], v[14:17], 0
	s_mov_b64 s[0:1], 0xc0
	v_or_b32_e32 v34, s12, v34
	s_mov_b64 s[12:13], -1
	s_waitcnt lgkmcnt(0)
	v_mfma_f32_16x16x32_bf16 v[22:25], v[22:25], v[18:21], 0
	s_waitcnt vmcnt(2)
	v_mfma_f32_16x16x32_bf16 v[44:47], v[26:29], v[14:17], 0
	v_mfma_f32_16x16x32_bf16 v[26:29], v[26:29], v[18:21], 0
	s_waitcnt vmcnt(1)
	v_mfma_f32_16x16x32_bf16 v[48:51], v[30:33], v[14:17], 0
	v_mfma_f32_16x16x32_bf16 v[30:33], v[30:33], v[18:21], 0
	s_waitcnt vmcnt(0)
	v_mfma_f32_16x16x32_bf16 v[14:17], v[36:39], v[14:17], 0
	v_mfma_f32_16x16x32_bf16 v[18:21], v[36:39], v[18:21], 0
	ds_read_b128 v[36:39], v12 offset:64
	ds_read_b128 v[52:55], v12 offset:8512
	global_load_dwordx4 v[64:67], v[64:65], off
	s_nop 0
	global_load_dwordx4 v[68:71], v[68:69], off
	s_waitcnt vmcnt(0) lgkmcnt(1)
	v_mfma_f32_16x16x32_bf16 v[14:17], v[68:71], v[36:39], v[14:17]
	global_load_dwordx4 v[56:59], v[8:9], off offset:64
	s_nop 0
	global_load_dwordx4 v[60:63], v[60:61], off
	s_waitcnt lgkmcnt(0)
	v_mfma_f32_16x16x32_bf16 v[18:21], v[68:71], v[52:55], v[18:21]
	v_lshl_add_u64 v[68:69], v[10:11], 0, s[6:7]
	s_waitcnt vmcnt(0)
	v_mfma_f32_16x16x32_bf16 v[44:47], v[60:63], v[36:39], v[44:47]
	v_mfma_f32_16x16x32_bf16 v[26:29], v[60:63], v[52:55], v[26:29]
	v_lshl_add_u64 v[60:61], v[68:69], 0, v[2:3]
	v_mfma_f32_16x16x32_bf16 v[48:51], v[64:67], v[36:39], v[48:51]
	v_mfma_f32_16x16x32_bf16 v[30:33], v[64:67], v[52:55], v[30:33]
	v_lshl_add_u64 v[64:65], v[68:69], 0, v[4:5]
	v_lshl_add_u64 v[68:69], v[68:69], 0, v[6:7]
	v_mfma_f32_16x16x32_bf16 v[40:43], v[56:59], v[36:39], v[40:43]
	v_mfma_f32_16x16x32_bf16 v[22:25], v[56:59], v[52:55], v[22:25]
	ds_read_b128 v[36:39], v12 offset:128
	ds_read_b128 v[52:55], v12 offset:8576
	global_load_dwordx4 v[64:67], v[64:65], off
	s_nop 0
	global_load_dwordx4 v[68:71], v[68:69], off
	s_waitcnt vmcnt(0) lgkmcnt(1)
	v_mfma_f32_16x16x32_bf16 v[14:17], v[68:71], v[36:39], v[14:17]
	global_load_dwordx4 v[56:59], v[8:9], off offset:128
	s_nop 0
	global_load_dwordx4 v[60:63], v[60:61], off
	s_waitcnt lgkmcnt(0)
	v_mfma_f32_16x16x32_bf16 v[18:21], v[68:71], v[52:55], v[18:21]
	v_lshl_add_u64 v[68:69], v[10:11], 0, s[0:1]
	s_mov_b64 s[0:1], 0x100
	s_waitcnt vmcnt(0)
	v_mfma_f32_16x16x32_bf16 v[44:47], v[60:63], v[36:39], v[44:47]
	v_mfma_f32_16x16x32_bf16 v[26:29], v[60:63], v[52:55], v[26:29]
	v_lshl_add_u64 v[60:61], v[68:69], 0, v[2:3]
	v_mfma_f32_16x16x32_bf16 v[48:51], v[64:67], v[36:39], v[48:51]
	v_mfma_f32_16x16x32_bf16 v[30:33], v[64:67], v[52:55], v[30:33]
	v_lshl_add_u64 v[64:65], v[68:69], 0, v[4:5]
	v_lshl_add_u64 v[68:69], v[68:69], 0, v[6:7]
	v_mfma_f32_16x16x32_bf16 v[40:43], v[56:59], v[36:39], v[40:43]
	v_mfma_f32_16x16x32_bf16 v[22:25], v[56:59], v[52:55], v[22:25]
	ds_read_b128 v[36:39], v12 offset:192
	ds_read_b128 v[52:55], v12 offset:8640
	global_load_dwordx4 v[64:67], v[64:65], off
	s_nop 0
	global_load_dwordx4 v[68:71], v[68:69], off
	s_waitcnt vmcnt(0) lgkmcnt(1)
	v_mfma_f32_16x16x32_bf16 v[14:17], v[68:71], v[36:39], v[14:17]
	global_load_dwordx4 v[56:59], v[8:9], off offset:192
	s_nop 0
	global_load_dwordx4 v[60:63], v[60:61], off
	s_waitcnt lgkmcnt(0)
	v_mfma_f32_16x16x32_bf16 v[18:21], v[68:71], v[52:55], v[18:21]
	v_lshl_add_u64 v[68:69], v[10:11], 0, s[0:1]
	s_mov_b64 s[0:1], 0x140
	s_waitcnt vmcnt(0)
	v_mfma_f32_16x16x32_bf16 v[44:47], v[60:63], v[36:39], v[44:47]
	v_mfma_f32_16x16x32_bf16 v[26:29], v[60:63], v[52:55], v[26:29]
	v_lshl_add_u64 v[60:61], v[68:69], 0, v[2:3]
	v_mfma_f32_16x16x32_bf16 v[48:51], v[64:67], v[36:39], v[48:51]
	v_mfma_f32_16x16x32_bf16 v[30:33], v[64:67], v[52:55], v[30:33]
	v_lshl_add_u64 v[64:65], v[68:69], 0, v[4:5]
	v_lshl_add_u64 v[68:69], v[68:69], 0, v[6:7]
	v_mfma_f32_16x16x32_bf16 v[40:43], v[56:59], v[36:39], v[40:43]
	v_mfma_f32_16x16x32_bf16 v[22:25], v[56:59], v[52:55], v[22:25]
	ds_read_b128 v[36:39], v12 offset:256
	ds_read_b128 v[52:55], v12 offset:8704
	global_load_dwordx4 v[64:67], v[64:65], off
	s_nop 0
	global_load_dwordx4 v[68:71], v[68:69], off
	s_waitcnt vmcnt(0) lgkmcnt(1)
	v_mfma_f32_16x16x32_bf16 v[14:17], v[68:71], v[36:39], v[14:17]
	global_load_dwordx4 v[56:59], v[8:9], off offset:256
	s_nop 0
	global_load_dwordx4 v[60:63], v[60:61], off
	s_waitcnt lgkmcnt(0)
	v_mfma_f32_16x16x32_bf16 v[18:21], v[68:71], v[52:55], v[18:21]
	v_lshl_add_u64 v[68:69], v[10:11], 0, s[0:1]
	s_mov_b64 s[0:1], 0x180
	s_waitcnt vmcnt(0)
	v_mfma_f32_16x16x32_bf16 v[44:47], v[60:63], v[36:39], v[44:47]
	v_mfma_f32_16x16x32_bf16 v[26:29], v[60:63], v[52:55], v[26:29]
	v_lshl_add_u64 v[60:61], v[68:69], 0, v[2:3]
	v_mfma_f32_16x16x32_bf16 v[48:51], v[64:67], v[36:39], v[48:51]
	v_mfma_f32_16x16x32_bf16 v[30:33], v[64:67], v[52:55], v[30:33]
	v_lshl_add_u64 v[64:65], v[68:69], 0, v[4:5]
	v_lshl_add_u64 v[68:69], v[68:69], 0, v[6:7]
	v_mfma_f32_16x16x32_bf16 v[40:43], v[56:59], v[36:39], v[40:43]
	v_mfma_f32_16x16x32_bf16 v[22:25], v[56:59], v[52:55], v[22:25]
	ds_read_b128 v[36:39], v12 offset:320
	ds_read_b128 v[52:55], v12 offset:8768
	global_load_dwordx4 v[64:67], v[64:65], off
	s_nop 0
	global_load_dwordx4 v[68:71], v[68:69], off
	s_waitcnt vmcnt(0) lgkmcnt(1)
	v_mfma_f32_16x16x32_bf16 v[14:17], v[68:71], v[36:39], v[14:17]
	global_load_dwordx4 v[56:59], v[8:9], off offset:320
	s_nop 0
	global_load_dwordx4 v[60:63], v[60:61], off
	s_waitcnt lgkmcnt(0)
	v_mfma_f32_16x16x32_bf16 v[18:21], v[68:71], v[52:55], v[18:21]
	v_lshl_add_u64 v[68:69], v[10:11], 0, s[0:1]
	s_mov_b64 s[0:1], 0x1c0
	s_waitcnt vmcnt(0)
	v_mfma_f32_16x16x32_bf16 v[44:47], v[60:63], v[36:39], v[44:47]
	v_mfma_f32_16x16x32_bf16 v[26:29], v[60:63], v[52:55], v[26:29]
	v_lshl_add_u64 v[60:61], v[68:69], 0, v[2:3]
	v_mfma_f32_16x16x32_bf16 v[48:51], v[64:67], v[36:39], v[48:51]
	v_mfma_f32_16x16x32_bf16 v[30:33], v[64:67], v[52:55], v[30:33]
	v_lshl_add_u64 v[64:65], v[68:69], 0, v[4:5]
	v_lshl_add_u64 v[68:69], v[68:69], 0, v[6:7]
	v_mfma_f32_16x16x32_bf16 v[40:43], v[56:59], v[36:39], v[40:43]
	v_mfma_f32_16x16x32_bf16 v[22:25], v[56:59], v[52:55], v[22:25]
	ds_read_b128 v[36:39], v12 offset:384
	ds_read_b128 v[52:55], v12 offset:8832
	global_load_dwordx4 v[56:59], v[8:9], off offset:384
	s_nop 0
	global_load_dwordx4 v[60:63], v[60:61], off
	s_waitcnt vmcnt(1) lgkmcnt(1)
	v_mfma_f32_16x16x32_bf16 v[40:43], v[56:59], v[36:39], v[40:43]
	global_load_dwordx4 v[64:67], v[64:65], off
	s_nop 0
	global_load_dwordx4 v[68:71], v[68:69], off
	s_waitcnt vmcnt(2)
	v_mfma_f32_16x16x32_bf16 v[44:47], v[60:63], v[36:39], v[44:47]
	s_waitcnt vmcnt(1)
	v_mfma_f32_16x16x32_bf16 v[48:51], v[64:67], v[36:39], v[48:51]
	s_waitcnt vmcnt(0)
	v_mfma_f32_16x16x32_bf16 v[36:39], v[68:71], v[36:39], v[14:17]
	s_nop 2
	v_lshl_add_u64 v[16:17], v[10:11], 0, s[0:1]
	v_lshl_add_u64 v[2:3], v[16:17], 0, v[2:3]
	v_lshl_add_u64 v[6:7], v[16:17], 0, v[6:7]
	s_waitcnt lgkmcnt(0)
	v_mfma_f32_16x16x32_bf16 v[22:25], v[56:59], v[52:55], v[22:25]
	s_cselect_b64 s[0:1], -1, 0
	s_and_b64 vcc, exec, s[0:1]
	v_mfma_f32_16x16x32_bf16 v[56:59], v[60:63], v[52:55], v[26:29]
	v_mfma_f32_16x16x32_bf16 v[60:63], v[64:67], v[52:55], v[30:33]
	v_mfma_f32_16x16x32_bf16 v[52:55], v[68:71], v[52:55], v[18:21]
	ds_read_b128 v[64:67], v12 offset:448
	ds_read_b128 v[68:71], v12 offset:8896
	global_load_dwordx4 v[8:11], v[8:9], off offset:448
	s_nop 0
	global_load_dwordx4 v[12:15], v[2:3], off
	global_load_dwordx4 v[72:75], v[6:7], off
	v_lshl_add_u64 v[2:3], v[16:17], 0, v[4:5]
	global_load_dwordx4 v[2:5], v[2:3], off
	s_waitcnt vmcnt(3) lgkmcnt(1)
	v_mfma_f32_16x16x32_bf16 v[30:33], v[8:11], v[64:67], v[40:43]
	s_nop 2
	v_or_b32_e32 v43, 3, v128
	s_waitcnt lgkmcnt(0)
	v_mfma_f32_16x16x32_bf16 v[26:29], v[8:11], v[68:71], v[22:25]
	s_waitcnt vmcnt(1)
	v_mfma_f32_16x16x32_bf16 v[6:9], v[72:75], v[64:67], v[36:39]
	s_nop 2
	v_add_u32_e32 v39, v34, v35
	v_ashrrev_i32_e32 v34, 9, v39
	v_mfma_f32_16x16x32_bf16 v[22:25], v[12:15], v[64:67], v[44:47]
	v_bfi_b32 v34, -4, v34, v129
	v_ashrrev_i32_e32 v35, 31, v34
	v_lshlrev_b64 v[36:37], 15, v[34:35]
	v_mfma_f32_16x16x32_bf16 v[18:21], v[12:15], v[68:71], v[56:59]
	v_lshrrev_b32_e32 v47, 2, v39
	v_and_b32_e32 v40, 0x1fb, v47
	v_lshlrev_b32_e32 v38, 1, v39
	s_waitcnt vmcnt(0)
	v_mfma_f32_16x16x32_bf16 v[14:17], v[2:5], v[64:67], v[48:51]
	v_lshrrev_b32_e32 v34, 3, v39
	v_bfe_u32 v35, v39, 2, 2
	v_lshlrev_b32_e32 v39, 2, v40
	v_mfma_f32_16x16x32_bf16 v[10:13], v[2:5], v[68:71], v[60:63]
	v_or_b32_e32 v45, 1, v128
	v_or_b32_e32 v44, 2, v128
	v_and_b32_e32 v46, 0xe00, v38
	v_mfma_f32_16x16x32_bf16 v[2:5], v[72:75], v[68:71], v[52:55]
	v_and_or_b32 v40, v34, 4, v35
	v_and_b32_e32 v41, 0xc0, v39
	v_lshl_add_u64 v[34:35], v[36:37], 1, s[48:49]
	s_cbranch_vccz .LBB0_599
	v_or3_b32 v42, v128, v46, v41
	v_lshlrev_b32_e32 v48, 4, v42
	v_mov_b32_e32 v49, v1
	v_lshl_add_u64 v[48:49], v[34:35], 0, v[48:49]
	v_lshlrev_b32_e32 v50, 1, v40
	v_mov_b32_e32 v51, v1
	v_cvt_pk_bf16_f32 v39, v30, s0
	v_lshl_add_u64 v[48:49], v[48:49], 0, v[50:51]
	v_or3_b32 v42, v45, v46, v41
	global_store_short v[48:49], v39, off
	v_lshlrev_b32_e32 v48, 4, v42
	v_mov_b32_e32 v49, v1
	v_lshl_add_u64 v[48:49], v[34:35], 0, v[48:49]
	v_cvt_pk_bf16_f32 v39, v31, s0
	v_lshl_add_u64 v[48:49], v[48:49], 0, v[50:51]
	v_or3_b32 v42, v44, v46, v41
	global_store_short v[48:49], v39, off
	v_lshlrev_b32_e32 v48, 4, v42
	v_mov_b32_e32 v49, v1
	v_lshl_add_u64 v[48:49], v[34:35], 0, v[48:49]
	v_cvt_pk_bf16_f32 v39, v32, s0
	v_lshl_add_u64 v[48:49], v[48:49], 0, v[50:51]
	v_or3_b32 v42, v43, v46, v41
	global_store_short v[48:49], v39, off
	v_lshlrev_b32_e32 v48, 4, v42
	v_mov_b32_e32 v49, v1
	v_lshl_add_u64 v[48:49], v[34:35], 0, v[48:49]
	v_cvt_pk_bf16_f32 v39, v33, s0
	v_lshl_add_u64 v[48:49], v[48:49], 0, v[50:51]
	global_store_short v[48:49], v39, off
	s_mov_b64 s[12:13], 0

.LBB0_702:
	s_or_b64 exec, exec, s[14:15]
	s_waitcnt lgkmcnt(0)
	s_add_u32 s69, s86, s46
	s_addc_u32 s79, s87, s47
	s_movk_i32 s14, 0x104
	s_cmp_gt_i32 s53, -1
	s_mov_b32 s94, s53
	v_mul_lo_u32 v0, v37, s14
	s_cselect_b64 s[46:47], -1, 0
	s_lshl_b64 s[14:15], s[94:95], 3
	v_readlane_b32 s44, v253, 0
	v_readlane_b32 s45, v253, 1
	s_add_u32 s70, s44, s14
	s_addc_u32 s71, s45, s15
	s_ashr_i32 s55, s54, 31
	s_ashr_i32 s49, s48, 31
	v_lshl_add_u32 v0, v36, 2, v0
	s_cmp_eq_u32 s52, 0
	s_waitcnt vmcnt(0)
	ds_write2_b32 v0, v6, v7 offset1:1
	ds_write2_b32 v0, v8, v9 offset0:2 offset1:3
	v_add_u32_e32 v6, 0x1040, v0
	s_cselect_b64 s[44:45], -1, 0
	s_add_i32 s14, s68, 0xfffff540
	ds_write2_b32 v6, v2, v3 offset1:1
	v_add_u32_e32 v2, 0x1048, v0
	s_lshr_b32 s14, s14, 6
	ds_write2_b32 v2, v4, v5 offset1:1
	v_add_u32_e32 v2, 0x2080, v0
	s_cmp_gt_i32 s78, 42
	ds_write2_b32 v2, v14, v15 offset1:1
	v_add_u32_e32 v2, 0x2088, v0
	s_cselect_b32 s14, s14, s78
	ds_write2_b32 v2, v16, v17 offset1:1
	v_add_u32_e32 v2, 0x30c0, v0
	v_add_u32_e32 v0, 0x30c8, v0
	s_cselect_b32 s15, 64, 0
	s_lshl_b32 s14, s14, 7
	ds_write2_b32 v0, v12, v13 offset1:1
	v_lshlrev_b32_e32 v0, 3, v35
	s_or_b32 s14, s14, s15
	s_lshl_b64 s[52:53], s[48:49], 1
	v_ashrrev_i32_e32 v13, 3, v35
	v_and_b32_e32 v12, 56, v0
	s_add_u32 s52, s69, s52
	s_addc_u32 s53, s79, s53
	v_lshlrev_b32_e32 v0, 1, v12
	v_add_u32_e32 v14, s68, v13
	v_cndmask_b32_e64 v4, 0, 1, s[46:47]
	ds_write2_b32 v2, v10, v11 offset1:1
	v_lshl_add_u64 v[2:3], s[52:53], 0, v[0:1]
	s_mov_b32 s100, s12
	s_cmpk_eq_u32 s12, 0x400
	s_cbranch_scc1 .Lmy_kb_do
	s_cmpk_eq_u32 s12, 0xac0
	s_cbranch_scc1 .Lmy_kb_do
	s_cmpk_eq_u32 s12, 0x800
	s_cbranch_scc0 .Lmy_kb_skip
